# P10 row pass hand-written: software-pipelined 3+3+2 row groups (register double buffer), sample rows as 9th-row stage, in-place z
# speedup vs baseline: 1.0005x; 1.0005x over previous
; __device__ __forceinline__ float bf2f(unsigned b) { return __uint_as_float(b << 16); }
; __device__ __forceinline__ void row_final2(const FinPtrs (&r)[NR], const float* g, int lane) {
;     f32x4 z[NR][4], x[NR][4]; u32x2 ra[NR][4], rb[NR][4]; float ss[NR];
; #pragma unroll
;     for (int k = 0; k < NR; ++k)
; #pragma unroll
;         for (int j = 0; j < 4; ++j) { { const u32x2 wv = ((const u32x2*)r[k].xin)[lane + 64 * j]; x[k][j] = (f32x4){bf2f(wv.x & 0xffffu), bf2f(wv.x >> 16), bf2f(wv.y & 0xffffu), bf2f(wv.y >> 16)}; }
;             ra[k][j] = ((const u32x2*)r[k].peb)[lane + 64 * j]; if (r[k].gls == nullptr) rb[k][j] = ((const u32x2*)r[k].glb)[lane + 64 * j]; }
; __global__ void __launch_bounds__(512, 2) fwd_kernel(Args args) {
;     ...
;         for (int m0 = gw; m0 < T; m0 += NR * NGW) { FinPtrs r[NR];
; #pragma unroll
;             for (int k = 0; k < NR; ++k) { const int m = (m0 + k * NGW < T) ? m0 + k * NGW : m0;
;                 r[k] = FinPtrs{UP + (size_t)m * FF2 + FF, UP + (size_t)m * FF2 + FF + D, nullptr, m < TP ? nullptr : GLS + (size_t)(m - TP) * D, UP + (size_t)m * FF2, out + O_Y + (size_t)m * D}; }
.LBB0_1207:
	s_cmp_lt_i32 s94, 11
	s_cselect_b64 s[2:3], -1, 0
	s_and_b64 s[0:1], s[2:3], s[0:1]
	s_and_b64 s[0:1], s[0:1], s[30:31]
	s_andn2_b64 vcc, exec, s[0:1]
	s_cbranch_vccnz .LBB0_1282
	v_readlane_b32 s12, v237, 4
	v_readlane_b32 s13, v237, 5
	v_readlane_b32 s14, v237, 6
	v_readlane_b32 s15, v237, 7
	v_lshlrev_b32_e32 v232, 3, v128
	v_lshlrev_b32_e32 v234, 4, v128
	v_add_u32_e32 v233, 0x1600, v232
	v_mov_b32_e32 v235, 0x358637bd
	v_xor_b32_e32 v216, 1, v128
	v_xor_b32_e32 v217, 2, v128
	v_xor_b32_e32 v218, 4, v128
	v_xor_b32_e32 v219, 8, v128
	v_xor_b32_e32 v220, 16, v128
	v_xor_b32_e32 v221, 32, v128
	v_lshlrev_b32_e32 v216, 2, v216
	v_lshlrev_b32_e32 v217, 2, v217
	v_lshlrev_b32_e32 v218, 2, v218
	v_lshlrev_b32_e32 v219, 2, v219
	v_lshlrev_b32_e32 v220, 2, v220
	v_lshlrev_b32_e32 v221, 2, v221
	s_mul_i32 s0, s34, 0x2c00
	s_mul_hi_u32 s1, s34, 0x2c00
	s_add_u32 s0, s0, 0x4300000
	s_addc_u32 s1, s1, 0
	s_add_u32 s36, s92, s0
	s_addc_u32 s37, s93, s1
	s_lshl_b32 s0, s34, 12
	s_add_u32 s38, s14, s0
	s_addc_u32 s39, s15, 0
	s_mov_b32 s40, 0xbfb8aa3b
	s_mov_b32 s41, 0xbfb8aa3b
	s_mov_b32 s42, 1.0
	s_mov_b32 s43, 1.0
	global_load_dwordx4 v[240:243], v234, s[12:13] offset:0
	global_load_dwordx4 v[244:247], v234, s[12:13] offset:1024
	global_load_dwordx4 v[248:251], v234, s[12:13] offset:2048
	global_load_dwordx4 v[252:255], v234, s[12:13] offset:3072
	global_load_dwordx2 v[0:1], v232, s[36:37] offset:0
	global_load_dwordx2 v[2:3], v232, s[36:37] offset:512
	global_load_dwordx2 v[4:5], v232, s[36:37] offset:1024
	global_load_dwordx2 v[6:7], v232, s[36:37] offset:1536
	global_load_dwordx2 v[8:9], v233, s[36:37] offset:0
	global_load_dwordx2 v[10:11], v233, s[36:37] offset:512
	global_load_dwordx2 v[12:13], v233, s[36:37] offset:1024
	global_load_dwordx2 v[14:15], v233, s[36:37] offset:1536
	global_load_dwordx2 v[16:17], v233, s[36:37] offset:2048
	global_load_dwordx2 v[18:19], v233, s[36:37] offset:2560
	global_load_dwordx2 v[20:21], v233, s[36:37] offset:3072
	global_load_dwordx2 v[22:23], v233, s[36:37] offset:3584
	s_add_u32 s36, s36, 0x1600000
	s_addc_u32 s37, s37, 0
	global_load_dwordx2 v[24:25], v232, s[36:37] offset:0
	global_load_dwordx2 v[26:27], v232, s[36:37] offset:512
	global_load_dwordx2 v[28:29], v232, s[36:37] offset:1024
	global_load_dwordx2 v[30:31], v232, s[36:37] offset:1536
	global_load_dwordx2 v[32:33], v233, s[36:37] offset:0
	global_load_dwordx2 v[34:35], v233, s[36:37] offset:512
	global_load_dwordx2 v[36:37], v233, s[36:37] offset:1024
	global_load_dwordx2 v[38:39], v233, s[36:37] offset:1536
	global_load_dwordx2 v[40:41], v233, s[36:37] offset:2048
	global_load_dwordx2 v[42:43], v233, s[36:37] offset:2560
	global_load_dwordx2 v[44:45], v233, s[36:37] offset:3072
	global_load_dwordx2 v[46:47], v233, s[36:37] offset:3584
	s_add_u32 s36, s36, 0x1600000
	s_addc_u32 s37, s37, 0
	global_load_dwordx2 v[48:49], v232, s[36:37] offset:0
	global_load_dwordx2 v[50:51], v232, s[36:37] offset:512
	global_load_dwordx2 v[52:53], v232, s[36:37] offset:1024
	global_load_dwordx2 v[54:55], v232, s[36:37] offset:1536
	global_load_dwordx2 v[56:57], v233, s[36:37] offset:0
	global_load_dwordx2 v[58:59], v233, s[36:37] offset:512
	global_load_dwordx2 v[60:61], v233, s[36:37] offset:1024
	global_load_dwordx2 v[62:63], v233, s[36:37] offset:1536
	global_load_dwordx2 v[64:65], v233, s[36:37] offset:2048
	global_load_dwordx2 v[66:67], v233, s[36:37] offset:2560
	global_load_dwordx2 v[68:69], v233, s[36:37] offset:3072
	global_load_dwordx2 v[70:71], v233, s[36:37] offset:3584
	s_add_u32 s36, s36, 0x1600000
	s_addc_u32 s37, s37, 0
	global_load_dwordx2 v[72:73], v232, s[36:37] offset:0
	global_load_dwordx2 v[74:75], v232, s[36:37] offset:512
	global_load_dwordx2 v[76:77], v232, s[36:37] offset:1024
	global_load_dwordx2 v[78:79], v232, s[36:37] offset:1536
	global_load_dwordx2 v[80:81], v233, s[36:37] offset:0
	global_load_dwordx2 v[82:83], v233, s[36:37] offset:512
	global_load_dwordx2 v[84:85], v233, s[36:37] offset:1024
	global_load_dwordx2 v[86:87], v233, s[36:37] offset:1536
	global_load_dwordx2 v[88:89], v233, s[36:37] offset:2048
	global_load_dwordx2 v[90:91], v233, s[36:37] offset:2560
	global_load_dwordx2 v[92:93], v233, s[36:37] offset:3072
	global_load_dwordx2 v[94:95], v233, s[36:37] offset:3584
	s_add_u32 s36, s36, 0x1600000
	s_addc_u32 s37, s37, 0
	s_waitcnt vmcnt(12)
; __device__ __forceinline__ float bf2f(unsigned b) { return __uint_as_float(b << 16); }
; __device__ __forceinline__ float sigmoidf_(float x) { return __builtin_amdgcn_rcpf(1.f + __expf(-x)); }
; __device__ __forceinline__ void row_final2(const FinPtrs (&r)[NR], const float* g, int lane) {
;     ...
;     for (int k = 0; k < NR; ++k) { ss[k] = 0.f;
; #pragma unroll
;         for (int j = 0; j < 4; ++j) {
;             f32x4 pe, gl;
;             { const u32x2 a = ra[k][j]; pe = (f32x4){bf2f(a.x & 0xffffu), bf2f(a.x >> 16), bf2f(a.y & 0xffffu), bf2f(a.y >> 16)}; }
;             if (r[k].gls == nullptr) { const u32x2 b = rb[k][j]; gl = (f32x4){bf2f(b.x & 0xffffu), bf2f(b.x >> 16), bf2f(b.y & 0xffffu), bf2f(b.y >> 16)}; }
;             else { const float* gls = r[k].gls;
;                 gl = (((const f32x4*)gls)[lane + 64 * j] + ((const f32x4*)(gls + (size_t)TS * D))[lane + 64 * j]) + (((const f32x4*)(gls + (size_t)2 * TS * D))[lane + 64 * j] + ((const f32x4*)(gls + (size_t)3 * TS * D))[lane + 64 * j]); }
;             z[k][j] = (f32x4){pe.x * sigmoidf_(gl.x), pe.y * sigmoidf_(gl.y), pe.z * sigmoidf_(gl.z), pe.w * sigmoidf_(gl.w)};
;             ss[k] += (z[k][j].x * z[k][j].x + z[k][j].y * z[k][j].y) + (z[k][j].z * z[k][j].z + z[k][j].w * z[k][j].w);
	global_load_dwordx2 v[96:97], v232, s[36:37] offset:0
	global_load_dwordx2 v[98:99], v232, s[36:37] offset:512
	global_load_dwordx2 v[100:101], v232, s[36:37] offset:1024
	global_load_dwordx2 v[102:103], v232, s[36:37] offset:1536
	global_load_dwordx2 v[104:105], v233, s[36:37] offset:0
	global_load_dwordx2 v[106:107], v233, s[36:37] offset:512
	global_load_dwordx2 v[108:109], v233, s[36:37] offset:1024
	global_load_dwordx2 v[110:111], v233, s[36:37] offset:1536
	global_load_dwordx2 v[112:113], v233, s[36:37] offset:2048
	global_load_dwordx2 v[114:115], v233, s[36:37] offset:2560
	global_load_dwordx2 v[116:117], v233, s[36:37] offset:3072
	global_load_dwordx2 v[118:119], v233, s[36:37] offset:3584
	s_add_u32 s36, s36, 0x1600000
	s_addc_u32 s37, s37, 0
	global_load_dwordx2 v[120:121], v232, s[36:37] offset:0
	global_load_dwordx2 v[122:123], v232, s[36:37] offset:512
	global_load_dwordx2 v[124:125], v232, s[36:37] offset:1024
	global_load_dwordx2 v[126:127], v232, s[36:37] offset:1536
	global_load_dwordx2 v[128:129], v233, s[36:37] offset:0
	global_load_dwordx2 v[130:131], v233, s[36:37] offset:512
	global_load_dwordx2 v[132:133], v233, s[36:37] offset:1024
	global_load_dwordx2 v[134:135], v233, s[36:37] offset:1536
	global_load_dwordx2 v[136:137], v233, s[36:37] offset:2048
	global_load_dwordx2 v[138:139], v233, s[36:37] offset:2560
	global_load_dwordx2 v[140:141], v233, s[36:37] offset:3072
	global_load_dwordx2 v[142:143], v233, s[36:37] offset:3584
	s_add_u32 s36, s36, 0x1600000
	s_addc_u32 s37, s37, 0
	v_mov_b32_e32 v192, 0
	v_mov_b32_e32 v193, 0
	v_mov_b32_e32 v194, 0
	v_mov_b32_e32 v195, 0
	v_lshlrev_b32_e32 v222, 16, v16
	v_and_b32_e32 v223, 0xffff0000, v16
	v_lshlrev_b32_e32 v224, 16, v17
	v_and_b32_e32 v225, 0xffff0000, v17
	v_pk_mul_f32 v[222:223], v[222:223], s[40:41]
	v_pk_mul_f32 v[224:225], v[224:225], s[40:41]
	v_exp_f32_e32 v222, v222
	v_exp_f32_e32 v223, v223
	v_exp_f32_e32 v224, v224
	v_exp_f32_e32 v225, v225
	v_pk_add_f32 v[222:223], v[222:223], s[42:43]
	v_pk_add_f32 v[224:225], v[224:225], s[42:43]
	v_rcp_f32_e32 v222, v222
	v_rcp_f32_e32 v223, v223
	v_rcp_f32_e32 v224, v224
	v_rcp_f32_e32 v225, v225
	v_lshlrev_b32_e32 v226, 16, v8
	v_and_b32_e32 v227, 0xffff0000, v8
	v_lshlrev_b32_e32 v228, 16, v9
	v_and_b32_e32 v229, 0xffff0000, v9
	v_pk_mul_f32 v[8:9], v[222:223], v[226:227]
	v_pk_mul_f32 v[16:17], v[224:225], v[228:229]
	v_pk_fma_f32 v[192:193], v[8:9], v[8:9], v[192:193]
	v_pk_fma_f32 v[194:195], v[16:17], v[16:17], v[194:195]
	v_lshlrev_b32_e32 v222, 16, v18
	v_and_b32_e32 v223, 0xffff0000, v18
	v_lshlrev_b32_e32 v224, 16, v19
	v_and_b32_e32 v225, 0xffff0000, v19
	v_pk_mul_f32 v[222:223], v[222:223], s[40:41]
	v_pk_mul_f32 v[224:225], v[224:225], s[40:41]
	v_exp_f32_e32 v222, v222
	v_exp_f32_e32 v223, v223
	v_exp_f32_e32 v224, v224
	v_exp_f32_e32 v225, v225
	v_pk_add_f32 v[222:223], v[222:223], s[42:43]
	v_pk_add_f32 v[224:225], v[224:225], s[42:43]
	v_rcp_f32_e32 v222, v222
	v_rcp_f32_e32 v223, v223
	v_rcp_f32_e32 v224, v224
	v_rcp_f32_e32 v225, v225
	v_lshlrev_b32_e32 v226, 16, v10
	v_and_b32_e32 v227, 0xffff0000, v10
	v_lshlrev_b32_e32 v228, 16, v11
	v_and_b32_e32 v229, 0xffff0000, v11
	v_pk_mul_f32 v[10:11], v[222:223], v[226:227]
	v_pk_mul_f32 v[18:19], v[224:225], v[228:229]
	v_pk_fma_f32 v[192:193], v[10:11], v[10:11], v[192:193]
	v_pk_fma_f32 v[194:195], v[18:19], v[18:19], v[194:195]
	v_lshlrev_b32_e32 v222, 16, v20
	v_and_b32_e32 v223, 0xffff0000, v20
	v_lshlrev_b32_e32 v224, 16, v21
	v_and_b32_e32 v225, 0xffff0000, v21
	v_pk_mul_f32 v[222:223], v[222:223], s[40:41]
	v_pk_mul_f32 v[224:225], v[224:225], s[40:41]
	v_exp_f32_e32 v222, v222
	v_exp_f32_e32 v223, v223
	v_exp_f32_e32 v224, v224
	v_exp_f32_e32 v225, v225
	v_pk_add_f32 v[222:223], v[222:223], s[42:43]
	v_pk_add_f32 v[224:225], v[224:225], s[42:43]
	v_rcp_f32_e32 v222, v222
	v_rcp_f32_e32 v223, v223
	v_rcp_f32_e32 v224, v224
	v_rcp_f32_e32 v225, v225
	v_lshlrev_b32_e32 v226, 16, v12
	v_and_b32_e32 v227, 0xffff0000, v12
	v_lshlrev_b32_e32 v228, 16, v13
	v_and_b32_e32 v229, 0xffff0000, v13
	v_pk_mul_f32 v[12:13], v[222:223], v[226:227]
	v_pk_mul_f32 v[20:21], v[224:225], v[228:229]
	v_pk_fma_f32 v[192:193], v[12:13], v[12:13], v[192:193]
	v_pk_fma_f32 v[194:195], v[20:21], v[20:21], v[194:195]
	v_lshlrev_b32_e32 v222, 16, v22
	v_and_b32_e32 v223, 0xffff0000, v22
	v_lshlrev_b32_e32 v224, 16, v23
	v_and_b32_e32 v225, 0xffff0000, v23
	v_pk_mul_f32 v[222:223], v[222:223], s[40:41]
	v_pk_mul_f32 v[224:225], v[224:225], s[40:41]
	v_exp_f32_e32 v222, v222
	v_exp_f32_e32 v223, v223
	v_exp_f32_e32 v224, v224
	v_exp_f32_e32 v225, v225
	v_pk_add_f32 v[222:223], v[222:223], s[42:43]
	v_pk_add_f32 v[224:225], v[224:225], s[42:43]
	v_rcp_f32_e32 v222, v222
	v_rcp_f32_e32 v223, v223
	v_rcp_f32_e32 v224, v224
	v_rcp_f32_e32 v225, v225
	v_lshlrev_b32_e32 v226, 16, v14
	v_and_b32_e32 v227, 0xffff0000, v14
	v_lshlrev_b32_e32 v228, 16, v15
	v_and_b32_e32 v229, 0xffff0000, v15
	v_pk_mul_f32 v[14:15], v[222:223], v[226:227]
	v_pk_mul_f32 v[22:23], v[224:225], v[228:229]
	v_pk_fma_f32 v[192:193], v[14:15], v[14:15], v[192:193]
	v_pk_fma_f32 v[194:195], v[22:23], v[22:23], v[194:195]
	v_mov_b32_e32 v196, 0
	v_mov_b32_e32 v197, 0
	v_mov_b32_e32 v198, 0
	v_mov_b32_e32 v199, 0
	v_lshlrev_b32_e32 v222, 16, v40
	v_and_b32_e32 v223, 0xffff0000, v40
	v_lshlrev_b32_e32 v224, 16, v41
	v_and_b32_e32 v225, 0xffff0000, v41
	v_pk_mul_f32 v[222:223], v[222:223], s[40:41]
	v_pk_mul_f32 v[224:225], v[224:225], s[40:41]
	v_exp_f32_e32 v222, v222
	v_exp_f32_e32 v223, v223
	v_exp_f32_e32 v224, v224
	v_exp_f32_e32 v225, v225
	v_pk_add_f32 v[222:223], v[222:223], s[42:43]
; __device__ __forceinline__ float bf2f(unsigned b) { return __uint_as_float(b << 16); }
; __device__ __forceinline__ float sigmoidf_(float x) { return __builtin_amdgcn_rcpf(1.f + __expf(-x)); }
; __device__ __forceinline__ void row_final2(const FinPtrs (&r)[NR], const float* g, int lane) {
;     ...
;     for (int k = 0; k < NR; ++k) { ss[k] = 0.f;
; #pragma unroll
;         for (int j = 0; j < 4; ++j) {
;             f32x4 pe, gl;
;             { const u32x2 a = ra[k][j]; pe = (f32x4){bf2f(a.x & 0xffffu), bf2f(a.x >> 16), bf2f(a.y & 0xffffu), bf2f(a.y >> 16)}; }
;             if (r[k].gls == nullptr) { const u32x2 b = rb[k][j]; gl = (f32x4){bf2f(b.x & 0xffffu), bf2f(b.x >> 16), bf2f(b.y & 0xffffu), bf2f(b.y >> 16)}; }
;             else { const float* gls = r[k].gls;
;                 gl = (((const f32x4*)gls)[lane + 64 * j] + ((const f32x4*)(gls + (size_t)TS * D))[lane + 64 * j]) + (((const f32x4*)(gls + (size_t)2 * TS * D))[lane + 64 * j] + ((const f32x4*)(gls + (size_t)3 * TS * D))[lane + 64 * j]); }
;             z[k][j] = (f32x4){pe.x * sigmoidf_(gl.x), pe.y * sigmoidf_(gl.y), pe.z * sigmoidf_(gl.z), pe.w * sigmoidf_(gl.w)};
;             ss[k] += (z[k][j].x * z[k][j].x + z[k][j].y * z[k][j].y) + (z[k][j].z * z[k][j].z + z[k][j].w * z[k][j].w);
	v_pk_add_f32 v[224:225], v[224:225], s[42:43]
	v_rcp_f32_e32 v222, v222
	v_rcp_f32_e32 v223, v223
	v_rcp_f32_e32 v224, v224
	v_rcp_f32_e32 v225, v225
	v_lshlrev_b32_e32 v226, 16, v32
	v_and_b32_e32 v227, 0xffff0000, v32
	v_lshlrev_b32_e32 v228, 16, v33
	v_and_b32_e32 v229, 0xffff0000, v33
	v_pk_mul_f32 v[32:33], v[222:223], v[226:227]
	v_pk_mul_f32 v[40:41], v[224:225], v[228:229]
	v_pk_fma_f32 v[196:197], v[32:33], v[32:33], v[196:197]
	v_pk_fma_f32 v[198:199], v[40:41], v[40:41], v[198:199]
	v_lshlrev_b32_e32 v222, 16, v42
	v_and_b32_e32 v223, 0xffff0000, v42
	v_lshlrev_b32_e32 v224, 16, v43
	v_and_b32_e32 v225, 0xffff0000, v43
	v_pk_mul_f32 v[222:223], v[222:223], s[40:41]
	v_pk_mul_f32 v[224:225], v[224:225], s[40:41]
	v_exp_f32_e32 v222, v222
	v_exp_f32_e32 v223, v223
	v_exp_f32_e32 v224, v224
	v_exp_f32_e32 v225, v225
	v_pk_add_f32 v[222:223], v[222:223], s[42:43]
	v_pk_add_f32 v[224:225], v[224:225], s[42:43]
	v_rcp_f32_e32 v222, v222
	v_rcp_f32_e32 v223, v223
	v_rcp_f32_e32 v224, v224
	v_rcp_f32_e32 v225, v225
	v_lshlrev_b32_e32 v226, 16, v34
	v_and_b32_e32 v227, 0xffff0000, v34
	v_lshlrev_b32_e32 v228, 16, v35
	v_and_b32_e32 v229, 0xffff0000, v35
	v_pk_mul_f32 v[34:35], v[222:223], v[226:227]
	v_pk_mul_f32 v[42:43], v[224:225], v[228:229]
	v_pk_fma_f32 v[196:197], v[34:35], v[34:35], v[196:197]
	v_pk_fma_f32 v[198:199], v[42:43], v[42:43], v[198:199]
	v_lshlrev_b32_e32 v222, 16, v44
	v_and_b32_e32 v223, 0xffff0000, v44
	v_lshlrev_b32_e32 v224, 16, v45
	v_and_b32_e32 v225, 0xffff0000, v45
	v_pk_mul_f32 v[222:223], v[222:223], s[40:41]
	v_pk_mul_f32 v[224:225], v[224:225], s[40:41]
	v_exp_f32_e32 v222, v222
	v_exp_f32_e32 v223, v223
	v_exp_f32_e32 v224, v224
	v_exp_f32_e32 v225, v225
	v_pk_add_f32 v[222:223], v[222:223], s[42:43]
	v_pk_add_f32 v[224:225], v[224:225], s[42:43]
	v_rcp_f32_e32 v222, v222
	v_rcp_f32_e32 v223, v223
	v_rcp_f32_e32 v224, v224
	v_rcp_f32_e32 v225, v225
	v_lshlrev_b32_e32 v226, 16, v36
	v_and_b32_e32 v227, 0xffff0000, v36
	v_lshlrev_b32_e32 v228, 16, v37
	v_and_b32_e32 v229, 0xffff0000, v37
	v_pk_mul_f32 v[36:37], v[222:223], v[226:227]
	v_pk_mul_f32 v[44:45], v[224:225], v[228:229]
	v_pk_fma_f32 v[196:197], v[36:37], v[36:37], v[196:197]
	v_pk_fma_f32 v[198:199], v[44:45], v[44:45], v[198:199]
	v_lshlrev_b32_e32 v222, 16, v46
	v_and_b32_e32 v223, 0xffff0000, v46
	v_lshlrev_b32_e32 v224, 16, v47
	v_and_b32_e32 v225, 0xffff0000, v47
	v_pk_mul_f32 v[222:223], v[222:223], s[40:41]
	v_pk_mul_f32 v[224:225], v[224:225], s[40:41]
	v_exp_f32_e32 v222, v222
	v_exp_f32_e32 v223, v223
	v_exp_f32_e32 v224, v224
	v_exp_f32_e32 v225, v225
	v_pk_add_f32 v[222:223], v[222:223], s[42:43]
	v_pk_add_f32 v[224:225], v[224:225], s[42:43]
	v_rcp_f32_e32 v222, v222
	v_rcp_f32_e32 v223, v223
	v_rcp_f32_e32 v224, v224
	v_rcp_f32_e32 v225, v225
	v_lshlrev_b32_e32 v226, 16, v38
	v_and_b32_e32 v227, 0xffff0000, v38
	v_lshlrev_b32_e32 v228, 16, v39
	v_and_b32_e32 v229, 0xffff0000, v39
	v_pk_mul_f32 v[38:39], v[222:223], v[226:227]
	v_pk_mul_f32 v[46:47], v[224:225], v[228:229]
	v_pk_fma_f32 v[196:197], v[38:39], v[38:39], v[196:197]
	v_pk_fma_f32 v[198:199], v[46:47], v[46:47], v[198:199]
	v_mov_b32_e32 v200, 0
	v_mov_b32_e32 v201, 0
	v_mov_b32_e32 v202, 0
	v_mov_b32_e32 v203, 0
	v_lshlrev_b32_e32 v222, 16, v64
	v_and_b32_e32 v223, 0xffff0000, v64
	v_lshlrev_b32_e32 v224, 16, v65
	v_and_b32_e32 v225, 0xffff0000, v65
	v_pk_mul_f32 v[222:223], v[222:223], s[40:41]
	v_pk_mul_f32 v[224:225], v[224:225], s[40:41]
	v_exp_f32_e32 v222, v222
	v_exp_f32_e32 v223, v223
	v_exp_f32_e32 v224, v224
	v_exp_f32_e32 v225, v225
	v_pk_add_f32 v[222:223], v[222:223], s[42:43]
	v_pk_add_f32 v[224:225], v[224:225], s[42:43]
	v_rcp_f32_e32 v222, v222
	v_rcp_f32_e32 v223, v223
	v_rcp_f32_e32 v224, v224
	v_rcp_f32_e32 v225, v225
	v_lshlrev_b32_e32 v226, 16, v56
	v_and_b32_e32 v227, 0xffff0000, v56
	v_lshlrev_b32_e32 v228, 16, v57
	v_and_b32_e32 v229, 0xffff0000, v57
	v_pk_mul_f32 v[56:57], v[222:223], v[226:227]
	v_pk_mul_f32 v[64:65], v[224:225], v[228:229]
	v_pk_fma_f32 v[200:201], v[56:57], v[56:57], v[200:201]
	v_pk_fma_f32 v[202:203], v[64:65], v[64:65], v[202:203]
	v_lshlrev_b32_e32 v222, 16, v66
	v_and_b32_e32 v223, 0xffff0000, v66
	v_lshlrev_b32_e32 v224, 16, v67
	v_and_b32_e32 v225, 0xffff0000, v67
	v_pk_mul_f32 v[222:223], v[222:223], s[40:41]
	v_pk_mul_f32 v[224:225], v[224:225], s[40:41]
	v_exp_f32_e32 v222, v222
	v_exp_f32_e32 v223, v223
	v_exp_f32_e32 v224, v224
	v_exp_f32_e32 v225, v225
	v_pk_add_f32 v[222:223], v[222:223], s[42:43]
	v_pk_add_f32 v[224:225], v[224:225], s[42:43]
	v_rcp_f32_e32 v222, v222
	v_rcp_f32_e32 v223, v223
	v_rcp_f32_e32 v224, v224
	v_rcp_f32_e32 v225, v225
	v_lshlrev_b32_e32 v226, 16, v58
	v_and_b32_e32 v227, 0xffff0000, v58
	v_lshlrev_b32_e32 v228, 16, v59
	v_and_b32_e32 v229, 0xffff0000, v59
	v_pk_mul_f32 v[58:59], v[222:223], v[226:227]
	v_pk_mul_f32 v[66:67], v[224:225], v[228:229]
	v_pk_fma_f32 v[200:201], v[58:59], v[58:59], v[200:201]
	v_pk_fma_f32 v[202:203], v[66:67], v[66:67], v[202:203]
	v_lshlrev_b32_e32 v222, 16, v68
	v_and_b32_e32 v223, 0xffff0000, v68
	v_lshlrev_b32_e32 v224, 16, v69
	v_and_b32_e32 v225, 0xffff0000, v69
	v_pk_mul_f32 v[222:223], v[222:223], s[40:41]
	v_pk_mul_f32 v[224:225], v[224:225], s[40:41]
	v_exp_f32_e32 v222, v222
	v_exp_f32_e32 v223, v223
	v_exp_f32_e32 v224, v224
	v_exp_f32_e32 v225, v225
	v_pk_add_f32 v[222:223], v[222:223], s[42:43]
	v_pk_add_f32 v[224:225], v[224:225], s[42:43]
	v_rcp_f32_e32 v222, v222
	v_rcp_f32_e32 v223, v223
	v_rcp_f32_e32 v224, v224
	v_rcp_f32_e32 v225, v225
	v_lshlrev_b32_e32 v226, 16, v60
	v_and_b32_e32 v227, 0xffff0000, v60
	v_lshlrev_b32_e32 v228, 16, v61
; __device__ __forceinline__ void row_final2(const FinPtrs (&r)[NR], const float* g, int lane) {
;     ...
;             ss[k] += (z[k][j].x * z[k][j].x + z[k][j].y * z[k][j].y) + (z[k][j].z * z[k][j].z + z[k][j].w * z[k][j].w);
;         } }
; #pragma unroll
;     for (int o = 1; o < 64; o <<= 1) {
; #pragma unroll
;             for (int k = 0; k < NR; ++k) ss[k] += __shfl_xor(ss[k], o); }
; #pragma unroll
;     for (int k = 0; k < NR; ++k) { const float rs = rsqrtf(ss[k] * (1.f / D) + EPS);
; #pragma unroll
;         for (int j = 0; j < 4; ++j) { const f32x4 gv = ((const f32x4*)g)[lane + 64 * j]; ((f32x4*)r[k].yout)[lane + 64 * j] = x[k][j] + z[k][j] * rs * gv; } }
	v_and_b32_e32 v229, 0xffff0000, v61
	v_pk_mul_f32 v[60:61], v[222:223], v[226:227]
	v_pk_mul_f32 v[68:69], v[224:225], v[228:229]
	v_pk_fma_f32 v[200:201], v[60:61], v[60:61], v[200:201]
	v_pk_fma_f32 v[202:203], v[68:69], v[68:69], v[202:203]
	v_lshlrev_b32_e32 v222, 16, v70
	v_and_b32_e32 v223, 0xffff0000, v70
	v_lshlrev_b32_e32 v224, 16, v71
	v_and_b32_e32 v225, 0xffff0000, v71
	v_pk_mul_f32 v[222:223], v[222:223], s[40:41]
	v_pk_mul_f32 v[224:225], v[224:225], s[40:41]
	v_exp_f32_e32 v222, v222
	v_exp_f32_e32 v223, v223
	v_exp_f32_e32 v224, v224
	v_exp_f32_e32 v225, v225
	v_pk_add_f32 v[222:223], v[222:223], s[42:43]
	v_pk_add_f32 v[224:225], v[224:225], s[42:43]
	v_rcp_f32_e32 v222, v222
	v_rcp_f32_e32 v223, v223
	v_rcp_f32_e32 v224, v224
	v_rcp_f32_e32 v225, v225
	v_lshlrev_b32_e32 v226, 16, v62
	v_and_b32_e32 v227, 0xffff0000, v62
	v_lshlrev_b32_e32 v228, 16, v63
	v_and_b32_e32 v229, 0xffff0000, v63
	v_pk_mul_f32 v[62:63], v[222:223], v[226:227]
	v_pk_mul_f32 v[70:71], v[224:225], v[228:229]
	v_pk_fma_f32 v[200:201], v[62:63], v[62:63], v[200:201]
	v_pk_fma_f32 v[202:203], v[70:71], v[70:71], v[202:203]
	v_pk_add_f32 v[192:193], v[192:193], v[194:195]
	v_pk_add_f32 v[196:197], v[196:197], v[198:199]
	v_pk_add_f32 v[200:201], v[200:201], v[202:203]
	v_add_f32_e32 v204, v192, v193
	v_add_f32_e32 v205, v196, v197
	v_add_f32_e32 v206, v200, v201
	ds_bpermute_b32 v192, v216, v204
	ds_bpermute_b32 v196, v216, v205
	ds_bpermute_b32 v200, v216, v206
	s_waitcnt lgkmcnt(0)
	v_add_f32_e32 v204, v204, v192
	v_add_f32_e32 v205, v205, v196
	v_add_f32_e32 v206, v206, v200
	ds_bpermute_b32 v192, v217, v204
	ds_bpermute_b32 v196, v217, v205
	ds_bpermute_b32 v200, v217, v206
	s_waitcnt lgkmcnt(0)
	v_add_f32_e32 v204, v204, v192
	v_add_f32_e32 v205, v205, v196
	v_add_f32_e32 v206, v206, v200
	ds_bpermute_b32 v192, v218, v204
	ds_bpermute_b32 v196, v218, v205
	ds_bpermute_b32 v200, v218, v206
	s_waitcnt lgkmcnt(0)
	v_add_f32_e32 v204, v204, v192
	v_add_f32_e32 v205, v205, v196
	v_add_f32_e32 v206, v206, v200
	ds_bpermute_b32 v192, v219, v204
	ds_bpermute_b32 v196, v219, v205
	ds_bpermute_b32 v200, v219, v206
	s_waitcnt lgkmcnt(0)
	v_add_f32_e32 v204, v204, v192
	v_add_f32_e32 v205, v205, v196
	v_add_f32_e32 v206, v206, v200
	ds_bpermute_b32 v192, v220, v204
	ds_bpermute_b32 v196, v220, v205
	ds_bpermute_b32 v200, v220, v206
	s_waitcnt lgkmcnt(0)
	v_add_f32_e32 v204, v204, v192
	v_add_f32_e32 v205, v205, v196
	v_add_f32_e32 v206, v206, v200
	ds_bpermute_b32 v192, v221, v204
	ds_bpermute_b32 v196, v221, v205
	ds_bpermute_b32 v200, v221, v206
	s_waitcnt lgkmcnt(0)
	v_add_f32_e32 v204, v204, v192
	v_add_f32_e32 v205, v205, v196
	v_add_f32_e32 v206, v206, v200
	v_fmamk_f32 v204, v204, 0x3a800000, v235
	v_fmamk_f32 v205, v205, 0x3a800000, v235
	v_fmamk_f32 v206, v206, 0x3a800000, v235
	v_rsq_f32_e32 v188, v204
	v_rsq_f32_e32 v190, v205
	v_rsq_f32_e32 v186, v206
	s_nop 1
	v_lshlrev_b32_e32 v208, 16, v0
	v_and_b32_e32 v209, 0xffff0000, v0
	v_lshlrev_b32_e32 v210, 16, v1
	v_and_b32_e32 v211, 0xffff0000, v1
	v_pk_mul_f32 v[222:223], v[8:9], v[188:189] op_sel_hi:[1,0]
	v_pk_mul_f32 v[224:225], v[16:17], v[188:189] op_sel_hi:[1,0]
	v_pk_fma_f32 v[208:209], v[222:223], v[240:241], v[208:209]
	v_pk_fma_f32 v[210:211], v[224:225], v[242:243], v[210:211]
	global_store_dwordx4 v234, v[208:211], s[38:39] offset:0
	v_lshlrev_b32_e32 v212, 16, v2
	v_and_b32_e32 v213, 0xffff0000, v2
	v_lshlrev_b32_e32 v214, 16, v3
	v_and_b32_e32 v215, 0xffff0000, v3
	v_pk_mul_f32 v[222:223], v[10:11], v[188:189] op_sel_hi:[1,0]
	v_pk_mul_f32 v[224:225], v[18:19], v[188:189] op_sel_hi:[1,0]
	v_pk_fma_f32 v[212:213], v[222:223], v[244:245], v[212:213]
	v_pk_fma_f32 v[214:215], v[224:225], v[246:247], v[214:215]
	global_store_dwordx4 v234, v[212:215], s[38:39] offset:1024
	v_lshlrev_b32_e32 v208, 16, v4
	v_and_b32_e32 v209, 0xffff0000, v4
	v_lshlrev_b32_e32 v210, 16, v5
	v_and_b32_e32 v211, 0xffff0000, v5
	v_pk_mul_f32 v[222:223], v[12:13], v[188:189] op_sel_hi:[1,0]
	v_pk_mul_f32 v[224:225], v[20:21], v[188:189] op_sel_hi:[1,0]
	v_pk_fma_f32 v[208:209], v[222:223], v[248:249], v[208:209]
	v_pk_fma_f32 v[210:211], v[224:225], v[250:251], v[210:211]
	global_store_dwordx4 v234, v[208:211], s[38:39] offset:2048
	v_lshlrev_b32_e32 v212, 16, v6
	v_and_b32_e32 v213, 0xffff0000, v6
	v_lshlrev_b32_e32 v214, 16, v7
	v_and_b32_e32 v215, 0xffff0000, v7
	v_pk_mul_f32 v[222:223], v[14:15], v[188:189] op_sel_hi:[1,0]
	v_pk_mul_f32 v[224:225], v[22:23], v[188:189] op_sel_hi:[1,0]
	v_pk_fma_f32 v[212:213], v[222:223], v[252:253], v[212:213]
	v_pk_fma_f32 v[214:215], v[224:225], v[254:255], v[214:215]
	global_store_dwordx4 v234, v[212:215], s[38:39] offset:3072
	s_add_u32 s38, s38, 0x800000
	s_addc_u32 s39, s39, 0
	v_lshlrev_b32_e32 v208, 16, v24
	v_and_b32_e32 v209, 0xffff0000, v24
	v_lshlrev_b32_e32 v210, 16, v25
	v_and_b32_e32 v211, 0xffff0000, v25
	v_pk_mul_f32 v[222:223], v[32:33], v[190:191] op_sel_hi:[1,0]
	v_pk_mul_f32 v[224:225], v[40:41], v[190:191] op_sel_hi:[1,0]
	v_pk_fma_f32 v[208:209], v[222:223], v[240:241], v[208:209]
	v_pk_fma_f32 v[210:211], v[224:225], v[242:243], v[210:211]
	global_store_dwordx4 v234, v[208:211], s[38:39] offset:0
	v_lshlrev_b32_e32 v212, 16, v26
	v_and_b32_e32 v213, 0xffff0000, v26
	v_lshlrev_b32_e32 v214, 16, v27
	v_and_b32_e32 v215, 0xffff0000, v27
	v_pk_mul_f32 v[222:223], v[34:35], v[190:191] op_sel_hi:[1,0]
	v_pk_mul_f32 v[224:225], v[42:43], v[190:191] op_sel_hi:[1,0]
	v_pk_fma_f32 v[212:213], v[222:223], v[244:245], v[212:213]
	v_pk_fma_f32 v[214:215], v[224:225], v[246:247], v[214:215]
	global_store_dwordx4 v234, v[212:215], s[38:39] offset:1024
; __device__ __forceinline__ float bf2f(unsigned b) { return __uint_as_float(b << 16); }
; __device__ __forceinline__ float sigmoidf_(float x) { return __builtin_amdgcn_rcpf(1.f + __expf(-x)); }
; __device__ __forceinline__ void row_final2(const FinPtrs (&r)[NR], const float* g, int lane) {
;     ...
;     for (int k = 0; k < NR; ++k)
; #pragma unroll
;         for (int j = 0; j < 4; ++j) { { const u32x2 wv = ((const u32x2*)r[k].xin)[lane + 64 * j]; x[k][j] = (f32x4){bf2f(wv.x & 0xffffu), bf2f(wv.x >> 16), bf2f(wv.y & 0xffffu), bf2f(wv.y >> 16)}; }
;             ra[k][j] = ((const u32x2*)r[k].peb)[lane + 64 * j]; if (r[k].gls == nullptr) rb[k][j] = ((const u32x2*)r[k].glb)[lane + 64 * j]; }
; #pragma unroll
;     for (int k = 0; k < NR; ++k) { ss[k] = 0.f;
; #pragma unroll
;         for (int j = 0; j < 4; ++j) {
;             f32x4 pe, gl;
;             { const u32x2 a = ra[k][j]; pe = (f32x4){bf2f(a.x & 0xffffu), bf2f(a.x >> 16), bf2f(a.y & 0xffffu), bf2f(a.y >> 16)}; }
;             if (r[k].gls == nullptr) { const u32x2 b = rb[k][j]; gl = (f32x4){bf2f(b.x & 0xffffu), bf2f(b.x >> 16), bf2f(b.y & 0xffffu), bf2f(b.y >> 16)}; }
;             else { const float* gls = r[k].gls;
;                 gl = (((const f32x4*)gls)[lane + 64 * j] + ((const f32x4*)(gls + (size_t)TS * D))[lane + 64 * j]) + (((const f32x4*)(gls + (size_t)2 * TS * D))[lane + 64 * j] + ((const f32x4*)(gls + (size_t)3 * TS * D))[lane + 64 * j]); }
;             z[k][j] = (f32x4){pe.x * sigmoidf_(gl.x), pe.y * sigmoidf_(gl.y), pe.z * sigmoidf_(gl.z), pe.w * sigmoidf_(gl.w)};
;             ss[k] += (z[k][j].x * z[k][j].x + z[k][j].y * z[k][j].y) + (z[k][j].z * z[k][j].z + z[k][j].w * z[k][j].w);
	v_lshlrev_b32_e32 v208, 16, v28
	v_and_b32_e32 v209, 0xffff0000, v28
	v_lshlrev_b32_e32 v210, 16, v29
	v_and_b32_e32 v211, 0xffff0000, v29
	v_pk_mul_f32 v[222:223], v[36:37], v[190:191] op_sel_hi:[1,0]
	v_pk_mul_f32 v[224:225], v[44:45], v[190:191] op_sel_hi:[1,0]
	v_pk_fma_f32 v[208:209], v[222:223], v[248:249], v[208:209]
	v_pk_fma_f32 v[210:211], v[224:225], v[250:251], v[210:211]
	global_store_dwordx4 v234, v[208:211], s[38:39] offset:2048
	v_lshlrev_b32_e32 v212, 16, v30
	v_and_b32_e32 v213, 0xffff0000, v30
	v_lshlrev_b32_e32 v214, 16, v31
	v_and_b32_e32 v215, 0xffff0000, v31
	v_pk_mul_f32 v[222:223], v[38:39], v[190:191] op_sel_hi:[1,0]
	v_pk_mul_f32 v[224:225], v[46:47], v[190:191] op_sel_hi:[1,0]
	v_pk_fma_f32 v[212:213], v[222:223], v[252:253], v[212:213]
	v_pk_fma_f32 v[214:215], v[224:225], v[254:255], v[214:215]
	global_store_dwordx4 v234, v[212:215], s[38:39] offset:3072
	s_add_u32 s38, s38, 0x800000
	s_addc_u32 s39, s39, 0
	v_lshlrev_b32_e32 v208, 16, v48
	v_and_b32_e32 v209, 0xffff0000, v48
	v_lshlrev_b32_e32 v210, 16, v49
	v_and_b32_e32 v211, 0xffff0000, v49
	v_pk_mul_f32 v[222:223], v[56:57], v[186:187] op_sel_hi:[1,0]
	v_pk_mul_f32 v[224:225], v[64:65], v[186:187] op_sel_hi:[1,0]
	v_pk_fma_f32 v[208:209], v[222:223], v[240:241], v[208:209]
	v_pk_fma_f32 v[210:211], v[224:225], v[242:243], v[210:211]
	global_store_dwordx4 v234, v[208:211], s[38:39] offset:0
	v_lshlrev_b32_e32 v212, 16, v50
	v_and_b32_e32 v213, 0xffff0000, v50
	v_lshlrev_b32_e32 v214, 16, v51
	v_and_b32_e32 v215, 0xffff0000, v51
	v_pk_mul_f32 v[222:223], v[58:59], v[186:187] op_sel_hi:[1,0]
	v_pk_mul_f32 v[224:225], v[66:67], v[186:187] op_sel_hi:[1,0]
	v_pk_fma_f32 v[212:213], v[222:223], v[244:245], v[212:213]
	v_pk_fma_f32 v[214:215], v[224:225], v[246:247], v[214:215]
	global_store_dwordx4 v234, v[212:215], s[38:39] offset:1024
	v_lshlrev_b32_e32 v208, 16, v52
	v_and_b32_e32 v209, 0xffff0000, v52
	v_lshlrev_b32_e32 v210, 16, v53
	v_and_b32_e32 v211, 0xffff0000, v53
	v_pk_mul_f32 v[222:223], v[60:61], v[186:187] op_sel_hi:[1,0]
	v_pk_mul_f32 v[224:225], v[68:69], v[186:187] op_sel_hi:[1,0]
	v_pk_fma_f32 v[208:209], v[222:223], v[248:249], v[208:209]
	v_pk_fma_f32 v[210:211], v[224:225], v[250:251], v[210:211]
	global_store_dwordx4 v234, v[208:211], s[38:39] offset:2048
	v_lshlrev_b32_e32 v212, 16, v54
	v_and_b32_e32 v213, 0xffff0000, v54
	v_lshlrev_b32_e32 v214, 16, v55
	v_and_b32_e32 v215, 0xffff0000, v55
	v_pk_mul_f32 v[222:223], v[62:63], v[186:187] op_sel_hi:[1,0]
	v_pk_mul_f32 v[224:225], v[70:71], v[186:187] op_sel_hi:[1,0]
	v_pk_fma_f32 v[212:213], v[222:223], v[252:253], v[212:213]
	v_pk_fma_f32 v[214:215], v[224:225], v[254:255], v[214:215]
	global_store_dwordx4 v234, v[212:215], s[38:39] offset:3072
	s_add_u32 s38, s38, 0x800000
	s_addc_u32 s39, s39, 0
	s_waitcnt vmcnt(12)
	global_load_dwordx2 v[0:1], v232, s[36:37] offset:0
	global_load_dwordx2 v[2:3], v232, s[36:37] offset:512
	global_load_dwordx2 v[4:5], v232, s[36:37] offset:1024
	global_load_dwordx2 v[6:7], v232, s[36:37] offset:1536
	global_load_dwordx2 v[8:9], v233, s[36:37] offset:0
	global_load_dwordx2 v[10:11], v233, s[36:37] offset:512
	global_load_dwordx2 v[12:13], v233, s[36:37] offset:1024
	global_load_dwordx2 v[14:15], v233, s[36:37] offset:1536
	global_load_dwordx2 v[16:17], v233, s[36:37] offset:2048
	global_load_dwordx2 v[18:19], v233, s[36:37] offset:2560
	global_load_dwordx2 v[20:21], v233, s[36:37] offset:3072
	global_load_dwordx2 v[22:23], v233, s[36:37] offset:3584
	s_add_u32 s36, s36, 0x1600000
	s_addc_u32 s37, s37, 0
	global_load_dwordx2 v[24:25], v232, s[36:37] offset:0
	global_load_dwordx2 v[26:27], v232, s[36:37] offset:512
	global_load_dwordx2 v[28:29], v232, s[36:37] offset:1024
	global_load_dwordx2 v[30:31], v232, s[36:37] offset:1536
	global_load_dwordx2 v[32:33], v233, s[36:37] offset:0
	global_load_dwordx2 v[34:35], v233, s[36:37] offset:512
	global_load_dwordx2 v[36:37], v233, s[36:37] offset:1024
	global_load_dwordx2 v[38:39], v233, s[36:37] offset:1536
	global_load_dwordx2 v[40:41], v233, s[36:37] offset:2048
	global_load_dwordx2 v[42:43], v233, s[36:37] offset:2560
	global_load_dwordx2 v[44:45], v233, s[36:37] offset:3072
	global_load_dwordx2 v[46:47], v233, s[36:37] offset:3584
	s_add_u32 s36, s36, 0x1600000
	s_addc_u32 s37, s37, 0
	v_mov_b32_e32 v192, 0
	v_mov_b32_e32 v193, 0
	v_mov_b32_e32 v194, 0
	v_mov_b32_e32 v195, 0
	v_lshlrev_b32_e32 v222, 16, v88
	v_and_b32_e32 v223, 0xffff0000, v88
	v_lshlrev_b32_e32 v224, 16, v89
	v_and_b32_e32 v225, 0xffff0000, v89
	v_pk_mul_f32 v[222:223], v[222:223], s[40:41]
	v_pk_mul_f32 v[224:225], v[224:225], s[40:41]
	v_exp_f32_e32 v222, v222
	v_exp_f32_e32 v223, v223
	v_exp_f32_e32 v224, v224
	v_exp_f32_e32 v225, v225
	v_pk_add_f32 v[222:223], v[222:223], s[42:43]
	v_pk_add_f32 v[224:225], v[224:225], s[42:43]
	v_rcp_f32_e32 v222, v222
	v_rcp_f32_e32 v223, v223
	v_rcp_f32_e32 v224, v224
	v_rcp_f32_e32 v225, v225
	v_lshlrev_b32_e32 v226, 16, v80
	v_and_b32_e32 v227, 0xffff0000, v80
	v_lshlrev_b32_e32 v228, 16, v81
	v_and_b32_e32 v229, 0xffff0000, v81
	v_pk_mul_f32 v[80:81], v[222:223], v[226:227]
	v_pk_mul_f32 v[88:89], v[224:225], v[228:229]
	v_pk_fma_f32 v[192:193], v[80:81], v[80:81], v[192:193]
	v_pk_fma_f32 v[194:195], v[88:89], v[88:89], v[194:195]
	v_lshlrev_b32_e32 v222, 16, v90
	v_and_b32_e32 v223, 0xffff0000, v90
	v_lshlrev_b32_e32 v224, 16, v91
	v_and_b32_e32 v225, 0xffff0000, v91
	v_pk_mul_f32 v[222:223], v[222:223], s[40:41]
	v_pk_mul_f32 v[224:225], v[224:225], s[40:41]
	v_exp_f32_e32 v222, v222
	v_exp_f32_e32 v223, v223
	v_exp_f32_e32 v224, v224
	v_exp_f32_e32 v225, v225
	v_pk_add_f32 v[222:223], v[222:223], s[42:43]
; __device__ __forceinline__ float bf2f(unsigned b) { return __uint_as_float(b << 16); }
; __device__ __forceinline__ float sigmoidf_(float x) { return __builtin_amdgcn_rcpf(1.f + __expf(-x)); }
; __device__ __forceinline__ void row_final2(const FinPtrs (&r)[NR], const float* g, int lane) {
;     ...
;     for (int k = 0; k < NR; ++k) { ss[k] = 0.f;
; #pragma unroll
;         for (int j = 0; j < 4; ++j) {
;             f32x4 pe, gl;
;             { const u32x2 a = ra[k][j]; pe = (f32x4){bf2f(a.x & 0xffffu), bf2f(a.x >> 16), bf2f(a.y & 0xffffu), bf2f(a.y >> 16)}; }
;             if (r[k].gls == nullptr) { const u32x2 b = rb[k][j]; gl = (f32x4){bf2f(b.x & 0xffffu), bf2f(b.x >> 16), bf2f(b.y & 0xffffu), bf2f(b.y >> 16)}; }
;             else { const float* gls = r[k].gls;
;                 gl = (((const f32x4*)gls)[lane + 64 * j] + ((const f32x4*)(gls + (size_t)TS * D))[lane + 64 * j]) + (((const f32x4*)(gls + (size_t)2 * TS * D))[lane + 64 * j] + ((const f32x4*)(gls + (size_t)3 * TS * D))[lane + 64 * j]); }
;             z[k][j] = (f32x4){pe.x * sigmoidf_(gl.x), pe.y * sigmoidf_(gl.y), pe.z * sigmoidf_(gl.z), pe.w * sigmoidf_(gl.w)};
;             ss[k] += (z[k][j].x * z[k][j].x + z[k][j].y * z[k][j].y) + (z[k][j].z * z[k][j].z + z[k][j].w * z[k][j].w);
	v_pk_add_f32 v[224:225], v[224:225], s[42:43]
	v_rcp_f32_e32 v222, v222
	v_rcp_f32_e32 v223, v223
	v_rcp_f32_e32 v224, v224
	v_rcp_f32_e32 v225, v225
	v_lshlrev_b32_e32 v226, 16, v82
	v_and_b32_e32 v227, 0xffff0000, v82
	v_lshlrev_b32_e32 v228, 16, v83
	v_and_b32_e32 v229, 0xffff0000, v83
	v_pk_mul_f32 v[82:83], v[222:223], v[226:227]
	v_pk_mul_f32 v[90:91], v[224:225], v[228:229]
	v_pk_fma_f32 v[192:193], v[82:83], v[82:83], v[192:193]
	v_pk_fma_f32 v[194:195], v[90:91], v[90:91], v[194:195]
	v_lshlrev_b32_e32 v222, 16, v92
	v_and_b32_e32 v223, 0xffff0000, v92
	v_lshlrev_b32_e32 v224, 16, v93
	v_and_b32_e32 v225, 0xffff0000, v93
	v_pk_mul_f32 v[222:223], v[222:223], s[40:41]
	v_pk_mul_f32 v[224:225], v[224:225], s[40:41]
	v_exp_f32_e32 v222, v222
	v_exp_f32_e32 v223, v223
	v_exp_f32_e32 v224, v224
	v_exp_f32_e32 v225, v225
	v_pk_add_f32 v[222:223], v[222:223], s[42:43]
	v_pk_add_f32 v[224:225], v[224:225], s[42:43]
	v_rcp_f32_e32 v222, v222
	v_rcp_f32_e32 v223, v223
	v_rcp_f32_e32 v224, v224
	v_rcp_f32_e32 v225, v225
	v_lshlrev_b32_e32 v226, 16, v84
	v_and_b32_e32 v227, 0xffff0000, v84
	v_lshlrev_b32_e32 v228, 16, v85
	v_and_b32_e32 v229, 0xffff0000, v85
	v_pk_mul_f32 v[84:85], v[222:223], v[226:227]
	v_pk_mul_f32 v[92:93], v[224:225], v[228:229]
	v_pk_fma_f32 v[192:193], v[84:85], v[84:85], v[192:193]
	v_pk_fma_f32 v[194:195], v[92:93], v[92:93], v[194:195]
	v_lshlrev_b32_e32 v222, 16, v94
	v_and_b32_e32 v223, 0xffff0000, v94
	v_lshlrev_b32_e32 v224, 16, v95
	v_and_b32_e32 v225, 0xffff0000, v95
	v_pk_mul_f32 v[222:223], v[222:223], s[40:41]
	v_pk_mul_f32 v[224:225], v[224:225], s[40:41]
	v_exp_f32_e32 v222, v222
	v_exp_f32_e32 v223, v223
	v_exp_f32_e32 v224, v224
	v_exp_f32_e32 v225, v225
	v_pk_add_f32 v[222:223], v[222:223], s[42:43]
	v_pk_add_f32 v[224:225], v[224:225], s[42:43]
	v_rcp_f32_e32 v222, v222
	v_rcp_f32_e32 v223, v223
	v_rcp_f32_e32 v224, v224
	v_rcp_f32_e32 v225, v225
	v_lshlrev_b32_e32 v226, 16, v86
	v_and_b32_e32 v227, 0xffff0000, v86
	v_lshlrev_b32_e32 v228, 16, v87
	v_and_b32_e32 v229, 0xffff0000, v87
	v_pk_mul_f32 v[86:87], v[222:223], v[226:227]
	v_pk_mul_f32 v[94:95], v[224:225], v[228:229]
	v_pk_fma_f32 v[192:193], v[86:87], v[86:87], v[192:193]
	v_pk_fma_f32 v[194:195], v[94:95], v[94:95], v[194:195]
	v_mov_b32_e32 v196, 0
	v_mov_b32_e32 v197, 0
	v_mov_b32_e32 v198, 0
	v_mov_b32_e32 v199, 0
	v_lshlrev_b32_e32 v222, 16, v112
	v_and_b32_e32 v223, 0xffff0000, v112
	v_lshlrev_b32_e32 v224, 16, v113
	v_and_b32_e32 v225, 0xffff0000, v113
	v_pk_mul_f32 v[222:223], v[222:223], s[40:41]
	v_pk_mul_f32 v[224:225], v[224:225], s[40:41]
	v_exp_f32_e32 v222, v222
	v_exp_f32_e32 v223, v223
	v_exp_f32_e32 v224, v224
	v_exp_f32_e32 v225, v225
	v_pk_add_f32 v[222:223], v[222:223], s[42:43]
	v_pk_add_f32 v[224:225], v[224:225], s[42:43]
	v_rcp_f32_e32 v222, v222
	v_rcp_f32_e32 v223, v223
	v_rcp_f32_e32 v224, v224
	v_rcp_f32_e32 v225, v225
	v_lshlrev_b32_e32 v226, 16, v104
	v_and_b32_e32 v227, 0xffff0000, v104
	v_lshlrev_b32_e32 v228, 16, v105
	v_and_b32_e32 v229, 0xffff0000, v105
	v_pk_mul_f32 v[104:105], v[222:223], v[226:227]
	v_pk_mul_f32 v[112:113], v[224:225], v[228:229]
	v_pk_fma_f32 v[196:197], v[104:105], v[104:105], v[196:197]
	v_pk_fma_f32 v[198:199], v[112:113], v[112:113], v[198:199]
	v_lshlrev_b32_e32 v222, 16, v114
	v_and_b32_e32 v223, 0xffff0000, v114
	v_lshlrev_b32_e32 v224, 16, v115
	v_and_b32_e32 v225, 0xffff0000, v115
	v_pk_mul_f32 v[222:223], v[222:223], s[40:41]
	v_pk_mul_f32 v[224:225], v[224:225], s[40:41]
	v_exp_f32_e32 v222, v222
	v_exp_f32_e32 v223, v223
	v_exp_f32_e32 v224, v224
	v_exp_f32_e32 v225, v225
	v_pk_add_f32 v[222:223], v[222:223], s[42:43]
	v_pk_add_f32 v[224:225], v[224:225], s[42:43]
	v_rcp_f32_e32 v222, v222
	v_rcp_f32_e32 v223, v223
	v_rcp_f32_e32 v224, v224
	v_rcp_f32_e32 v225, v225
	v_lshlrev_b32_e32 v226, 16, v106
	v_and_b32_e32 v227, 0xffff0000, v106
	v_lshlrev_b32_e32 v228, 16, v107
	v_and_b32_e32 v229, 0xffff0000, v107
	v_pk_mul_f32 v[106:107], v[222:223], v[226:227]
	v_pk_mul_f32 v[114:115], v[224:225], v[228:229]
	v_pk_fma_f32 v[196:197], v[106:107], v[106:107], v[196:197]
	v_pk_fma_f32 v[198:199], v[114:115], v[114:115], v[198:199]
	v_lshlrev_b32_e32 v222, 16, v116
	v_and_b32_e32 v223, 0xffff0000, v116
	v_lshlrev_b32_e32 v224, 16, v117
	v_and_b32_e32 v225, 0xffff0000, v117
	v_pk_mul_f32 v[222:223], v[222:223], s[40:41]
	v_pk_mul_f32 v[224:225], v[224:225], s[40:41]
	v_exp_f32_e32 v222, v222
	v_exp_f32_e32 v223, v223
	v_exp_f32_e32 v224, v224
	v_exp_f32_e32 v225, v225
	v_pk_add_f32 v[222:223], v[222:223], s[42:43]
	v_pk_add_f32 v[224:225], v[224:225], s[42:43]
	v_rcp_f32_e32 v222, v222
	v_rcp_f32_e32 v223, v223
	v_rcp_f32_e32 v224, v224
	v_rcp_f32_e32 v225, v225
	v_lshlrev_b32_e32 v226, 16, v108
	v_and_b32_e32 v227, 0xffff0000, v108
	v_lshlrev_b32_e32 v228, 16, v109
	v_and_b32_e32 v229, 0xffff0000, v109
	v_pk_mul_f32 v[108:109], v[222:223], v[226:227]
	v_pk_mul_f32 v[116:117], v[224:225], v[228:229]
	v_pk_fma_f32 v[196:197], v[108:109], v[108:109], v[196:197]
	v_pk_fma_f32 v[198:199], v[116:117], v[116:117], v[198:199]
	v_lshlrev_b32_e32 v222, 16, v118
	v_and_b32_e32 v223, 0xffff0000, v118
	v_lshlrev_b32_e32 v224, 16, v119
	v_and_b32_e32 v225, 0xffff0000, v119
	v_pk_mul_f32 v[222:223], v[222:223], s[40:41]
	v_pk_mul_f32 v[224:225], v[224:225], s[40:41]
	v_exp_f32_e32 v222, v222
	v_exp_f32_e32 v223, v223
	v_exp_f32_e32 v224, v224
	v_exp_f32_e32 v225, v225
	v_pk_add_f32 v[222:223], v[222:223], s[42:43]
	v_pk_add_f32 v[224:225], v[224:225], s[42:43]
	v_rcp_f32_e32 v222, v222
	v_rcp_f32_e32 v223, v223
	v_rcp_f32_e32 v224, v224
	v_rcp_f32_e32 v225, v225
	v_lshlrev_b32_e32 v226, 16, v110
; __device__ __forceinline__ float bf2f(unsigned b) { return __uint_as_float(b << 16); }
; __device__ __forceinline__ float sigmoidf_(float x) { return __builtin_amdgcn_rcpf(1.f + __expf(-x)); }
; __device__ __forceinline__ void row_final2(const FinPtrs (&r)[NR], const float* g, int lane) {
;     ...
;     for (int k = 0; k < NR; ++k) { ss[k] = 0.f;
; #pragma unroll
;         for (int j = 0; j < 4; ++j) {
;             f32x4 pe, gl;
;             { const u32x2 a = ra[k][j]; pe = (f32x4){bf2f(a.x & 0xffffu), bf2f(a.x >> 16), bf2f(a.y & 0xffffu), bf2f(a.y >> 16)}; }
;             if (r[k].gls == nullptr) { const u32x2 b = rb[k][j]; gl = (f32x4){bf2f(b.x & 0xffffu), bf2f(b.x >> 16), bf2f(b.y & 0xffffu), bf2f(b.y >> 16)}; }
;             else { const float* gls = r[k].gls;
;                 gl = (((const f32x4*)gls)[lane + 64 * j] + ((const f32x4*)(gls + (size_t)TS * D))[lane + 64 * j]) + (((const f32x4*)(gls + (size_t)2 * TS * D))[lane + 64 * j] + ((const f32x4*)(gls + (size_t)3 * TS * D))[lane + 64 * j]); }
;             z[k][j] = (f32x4){pe.x * sigmoidf_(gl.x), pe.y * sigmoidf_(gl.y), pe.z * sigmoidf_(gl.z), pe.w * sigmoidf_(gl.w)};
;             ss[k] += (z[k][j].x * z[k][j].x + z[k][j].y * z[k][j].y) + (z[k][j].z * z[k][j].z + z[k][j].w * z[k][j].w);
;         } }
; #pragma unroll
;     for (int o = 1; o < 64; o <<= 1) {
; #pragma unroll
;             for (int k = 0; k < NR; ++k) ss[k] += __shfl_xor(ss[k], o); }
	v_and_b32_e32 v227, 0xffff0000, v110
	v_lshlrev_b32_e32 v228, 16, v111
	v_and_b32_e32 v229, 0xffff0000, v111
	v_pk_mul_f32 v[110:111], v[222:223], v[226:227]
	v_pk_mul_f32 v[118:119], v[224:225], v[228:229]
	v_pk_fma_f32 v[196:197], v[110:111], v[110:111], v[196:197]
	v_pk_fma_f32 v[198:199], v[118:119], v[118:119], v[198:199]
	v_mov_b32_e32 v200, 0
	v_mov_b32_e32 v201, 0
	v_mov_b32_e32 v202, 0
	v_mov_b32_e32 v203, 0
	v_lshlrev_b32_e32 v222, 16, v136
	v_and_b32_e32 v223, 0xffff0000, v136
	v_lshlrev_b32_e32 v224, 16, v137
	v_and_b32_e32 v225, 0xffff0000, v137
	v_pk_mul_f32 v[222:223], v[222:223], s[40:41]
	v_pk_mul_f32 v[224:225], v[224:225], s[40:41]
	v_exp_f32_e32 v222, v222
	v_exp_f32_e32 v223, v223
	v_exp_f32_e32 v224, v224
	v_exp_f32_e32 v225, v225
	v_pk_add_f32 v[222:223], v[222:223], s[42:43]
	v_pk_add_f32 v[224:225], v[224:225], s[42:43]
	v_rcp_f32_e32 v222, v222
	v_rcp_f32_e32 v223, v223
	v_rcp_f32_e32 v224, v224
	v_rcp_f32_e32 v225, v225
	v_lshlrev_b32_e32 v226, 16, v128
	v_and_b32_e32 v227, 0xffff0000, v128
	v_lshlrev_b32_e32 v228, 16, v129
	v_and_b32_e32 v229, 0xffff0000, v129
	v_pk_mul_f32 v[128:129], v[222:223], v[226:227]
	v_pk_mul_f32 v[136:137], v[224:225], v[228:229]
	v_pk_fma_f32 v[200:201], v[128:129], v[128:129], v[200:201]
	v_pk_fma_f32 v[202:203], v[136:137], v[136:137], v[202:203]
	v_lshlrev_b32_e32 v222, 16, v138
	v_and_b32_e32 v223, 0xffff0000, v138
	v_lshlrev_b32_e32 v224, 16, v139
	v_and_b32_e32 v225, 0xffff0000, v139
	v_pk_mul_f32 v[222:223], v[222:223], s[40:41]
	v_pk_mul_f32 v[224:225], v[224:225], s[40:41]
	v_exp_f32_e32 v222, v222
	v_exp_f32_e32 v223, v223
	v_exp_f32_e32 v224, v224
	v_exp_f32_e32 v225, v225
	v_pk_add_f32 v[222:223], v[222:223], s[42:43]
	v_pk_add_f32 v[224:225], v[224:225], s[42:43]
	v_rcp_f32_e32 v222, v222
	v_rcp_f32_e32 v223, v223
	v_rcp_f32_e32 v224, v224
	v_rcp_f32_e32 v225, v225
	v_lshlrev_b32_e32 v226, 16, v130
	v_and_b32_e32 v227, 0xffff0000, v130
	v_lshlrev_b32_e32 v228, 16, v131
	v_and_b32_e32 v229, 0xffff0000, v131
	v_pk_mul_f32 v[130:131], v[222:223], v[226:227]
	v_pk_mul_f32 v[138:139], v[224:225], v[228:229]
	v_pk_fma_f32 v[200:201], v[130:131], v[130:131], v[200:201]
	v_pk_fma_f32 v[202:203], v[138:139], v[138:139], v[202:203]
	v_lshlrev_b32_e32 v222, 16, v140
	v_and_b32_e32 v223, 0xffff0000, v140
	v_lshlrev_b32_e32 v224, 16, v141
	v_and_b32_e32 v225, 0xffff0000, v141
	v_pk_mul_f32 v[222:223], v[222:223], s[40:41]
	v_pk_mul_f32 v[224:225], v[224:225], s[40:41]
	v_exp_f32_e32 v222, v222
	v_exp_f32_e32 v223, v223
	v_exp_f32_e32 v224, v224
	v_exp_f32_e32 v225, v225
	v_pk_add_f32 v[222:223], v[222:223], s[42:43]
	v_pk_add_f32 v[224:225], v[224:225], s[42:43]
	v_rcp_f32_e32 v222, v222
	v_rcp_f32_e32 v223, v223
	v_rcp_f32_e32 v224, v224
	v_rcp_f32_e32 v225, v225
	v_lshlrev_b32_e32 v226, 16, v132
	v_and_b32_e32 v227, 0xffff0000, v132
	v_lshlrev_b32_e32 v228, 16, v133
	v_and_b32_e32 v229, 0xffff0000, v133
	v_pk_mul_f32 v[132:133], v[222:223], v[226:227]
	v_pk_mul_f32 v[140:141], v[224:225], v[228:229]
	v_pk_fma_f32 v[200:201], v[132:133], v[132:133], v[200:201]
	v_pk_fma_f32 v[202:203], v[140:141], v[140:141], v[202:203]
	v_lshlrev_b32_e32 v222, 16, v142
	v_and_b32_e32 v223, 0xffff0000, v142
	v_lshlrev_b32_e32 v224, 16, v143
	v_and_b32_e32 v225, 0xffff0000, v143
	v_pk_mul_f32 v[222:223], v[222:223], s[40:41]
	v_pk_mul_f32 v[224:225], v[224:225], s[40:41]
	v_exp_f32_e32 v222, v222
	v_exp_f32_e32 v223, v223
	v_exp_f32_e32 v224, v224
	v_exp_f32_e32 v225, v225
	v_pk_add_f32 v[222:223], v[222:223], s[42:43]
	v_pk_add_f32 v[224:225], v[224:225], s[42:43]
	v_rcp_f32_e32 v222, v222
	v_rcp_f32_e32 v223, v223
	v_rcp_f32_e32 v224, v224
	v_rcp_f32_e32 v225, v225
	v_lshlrev_b32_e32 v226, 16, v134
	v_and_b32_e32 v227, 0xffff0000, v134
	v_lshlrev_b32_e32 v228, 16, v135
	v_and_b32_e32 v229, 0xffff0000, v135
	v_pk_mul_f32 v[134:135], v[222:223], v[226:227]
	v_pk_mul_f32 v[142:143], v[224:225], v[228:229]
	v_pk_fma_f32 v[200:201], v[134:135], v[134:135], v[200:201]
	v_pk_fma_f32 v[202:203], v[142:143], v[142:143], v[202:203]
	v_pk_add_f32 v[192:193], v[192:193], v[194:195]
	v_pk_add_f32 v[196:197], v[196:197], v[198:199]
	v_pk_add_f32 v[200:201], v[200:201], v[202:203]
	v_add_f32_e32 v204, v192, v193
	v_add_f32_e32 v205, v196, v197
	v_add_f32_e32 v206, v200, v201
	ds_bpermute_b32 v192, v216, v204
	ds_bpermute_b32 v196, v216, v205
	ds_bpermute_b32 v200, v216, v206
	s_waitcnt lgkmcnt(0)
	v_add_f32_e32 v204, v204, v192
	v_add_f32_e32 v205, v205, v196
	v_add_f32_e32 v206, v206, v200
	ds_bpermute_b32 v192, v217, v204
	ds_bpermute_b32 v196, v217, v205
	ds_bpermute_b32 v200, v217, v206
	s_waitcnt lgkmcnt(0)
	v_add_f32_e32 v204, v204, v192
	v_add_f32_e32 v205, v205, v196
	v_add_f32_e32 v206, v206, v200
	ds_bpermute_b32 v192, v218, v204
	ds_bpermute_b32 v196, v218, v205
	ds_bpermute_b32 v200, v218, v206
	s_waitcnt lgkmcnt(0)
	v_add_f32_e32 v204, v204, v192
	v_add_f32_e32 v205, v205, v196
	v_add_f32_e32 v206, v206, v200
	ds_bpermute_b32 v192, v219, v204
	ds_bpermute_b32 v196, v219, v205
	ds_bpermute_b32 v200, v219, v206
	s_waitcnt lgkmcnt(0)
	v_add_f32_e32 v204, v204, v192
	v_add_f32_e32 v205, v205, v196
	v_add_f32_e32 v206, v206, v200
	ds_bpermute_b32 v192, v220, v204
	ds_bpermute_b32 v196, v220, v205
	ds_bpermute_b32 v200, v220, v206
	s_waitcnt lgkmcnt(0)
	v_add_f32_e32 v204, v204, v192
	v_add_f32_e32 v205, v205, v196
	v_add_f32_e32 v206, v206, v200
	ds_bpermute_b32 v192, v221, v204
	ds_bpermute_b32 v196, v221, v205
	ds_bpermute_b32 v200, v221, v206
	s_waitcnt lgkmcnt(0)
; __device__ __forceinline__ void row_final2(const FinPtrs (&r)[NR], const float* g, int lane) {
;     ...
;             for (int k = 0; k < NR; ++k) ss[k] += __shfl_xor(ss[k], o); }
; #pragma unroll
;     for (int k = 0; k < NR; ++k) { const float rs = rsqrtf(ss[k] * (1.f / D) + EPS);
; #pragma unroll
;         for (int j = 0; j < 4; ++j) { const f32x4 gv = ((const f32x4*)g)[lane + 64 * j]; ((f32x4*)r[k].yout)[lane + 64 * j] = x[k][j] + z[k][j] * rs * gv; } }
	v_add_f32_e32 v204, v204, v192
	v_add_f32_e32 v205, v205, v196
	v_add_f32_e32 v206, v206, v200
	v_fmamk_f32 v204, v204, 0x3a800000, v235
	v_fmamk_f32 v205, v205, 0x3a800000, v235
	v_fmamk_f32 v206, v206, 0x3a800000, v235
	v_rsq_f32_e32 v188, v204
	v_rsq_f32_e32 v190, v205
	v_rsq_f32_e32 v186, v206
	s_nop 1
	v_lshlrev_b32_e32 v208, 16, v72
	v_and_b32_e32 v209, 0xffff0000, v72
	v_lshlrev_b32_e32 v210, 16, v73
	v_and_b32_e32 v211, 0xffff0000, v73
	v_pk_mul_f32 v[222:223], v[80:81], v[188:189] op_sel_hi:[1,0]
	v_pk_mul_f32 v[224:225], v[88:89], v[188:189] op_sel_hi:[1,0]
	v_pk_fma_f32 v[208:209], v[222:223], v[240:241], v[208:209]
	v_pk_fma_f32 v[210:211], v[224:225], v[242:243], v[210:211]
	global_store_dwordx4 v234, v[208:211], s[38:39] offset:0
	v_lshlrev_b32_e32 v212, 16, v74
	v_and_b32_e32 v213, 0xffff0000, v74
	v_lshlrev_b32_e32 v214, 16, v75
	v_and_b32_e32 v215, 0xffff0000, v75
	v_pk_mul_f32 v[222:223], v[82:83], v[188:189] op_sel_hi:[1,0]
	v_pk_mul_f32 v[224:225], v[90:91], v[188:189] op_sel_hi:[1,0]
	v_pk_fma_f32 v[212:213], v[222:223], v[244:245], v[212:213]
	v_pk_fma_f32 v[214:215], v[224:225], v[246:247], v[214:215]
	global_store_dwordx4 v234, v[212:215], s[38:39] offset:1024
	v_lshlrev_b32_e32 v208, 16, v76
	v_and_b32_e32 v209, 0xffff0000, v76
	v_lshlrev_b32_e32 v210, 16, v77
	v_and_b32_e32 v211, 0xffff0000, v77
	v_pk_mul_f32 v[222:223], v[84:85], v[188:189] op_sel_hi:[1,0]
	v_pk_mul_f32 v[224:225], v[92:93], v[188:189] op_sel_hi:[1,0]
	v_pk_fma_f32 v[208:209], v[222:223], v[248:249], v[208:209]
	v_pk_fma_f32 v[210:211], v[224:225], v[250:251], v[210:211]
	global_store_dwordx4 v234, v[208:211], s[38:39] offset:2048
	v_lshlrev_b32_e32 v212, 16, v78
	v_and_b32_e32 v213, 0xffff0000, v78
	v_lshlrev_b32_e32 v214, 16, v79
	v_and_b32_e32 v215, 0xffff0000, v79
	v_pk_mul_f32 v[222:223], v[86:87], v[188:189] op_sel_hi:[1,0]
	v_pk_mul_f32 v[224:225], v[94:95], v[188:189] op_sel_hi:[1,0]
	v_pk_fma_f32 v[212:213], v[222:223], v[252:253], v[212:213]
	v_pk_fma_f32 v[214:215], v[224:225], v[254:255], v[214:215]
	global_store_dwordx4 v234, v[212:215], s[38:39] offset:3072
	s_add_u32 s38, s38, 0x800000
	s_addc_u32 s39, s39, 0
	v_lshlrev_b32_e32 v208, 16, v96
	v_and_b32_e32 v209, 0xffff0000, v96
	v_lshlrev_b32_e32 v210, 16, v97
	v_and_b32_e32 v211, 0xffff0000, v97
	v_pk_mul_f32 v[222:223], v[104:105], v[190:191] op_sel_hi:[1,0]
	v_pk_mul_f32 v[224:225], v[112:113], v[190:191] op_sel_hi:[1,0]
	v_pk_fma_f32 v[208:209], v[222:223], v[240:241], v[208:209]
	v_pk_fma_f32 v[210:211], v[224:225], v[242:243], v[210:211]
	global_store_dwordx4 v234, v[208:211], s[38:39] offset:0
	v_lshlrev_b32_e32 v212, 16, v98
	v_and_b32_e32 v213, 0xffff0000, v98
	v_lshlrev_b32_e32 v214, 16, v99
	v_and_b32_e32 v215, 0xffff0000, v99
	v_pk_mul_f32 v[222:223], v[106:107], v[190:191] op_sel_hi:[1,0]
	v_pk_mul_f32 v[224:225], v[114:115], v[190:191] op_sel_hi:[1,0]
	v_pk_fma_f32 v[212:213], v[222:223], v[244:245], v[212:213]
	v_pk_fma_f32 v[214:215], v[224:225], v[246:247], v[214:215]
	global_store_dwordx4 v234, v[212:215], s[38:39] offset:1024
	v_lshlrev_b32_e32 v208, 16, v100
	v_and_b32_e32 v209, 0xffff0000, v100
	v_lshlrev_b32_e32 v210, 16, v101
	v_and_b32_e32 v211, 0xffff0000, v101
	v_pk_mul_f32 v[222:223], v[108:109], v[190:191] op_sel_hi:[1,0]
	v_pk_mul_f32 v[224:225], v[116:117], v[190:191] op_sel_hi:[1,0]
	v_pk_fma_f32 v[208:209], v[222:223], v[248:249], v[208:209]
	v_pk_fma_f32 v[210:211], v[224:225], v[250:251], v[210:211]
	global_store_dwordx4 v234, v[208:211], s[38:39] offset:2048
	v_lshlrev_b32_e32 v212, 16, v102
	v_and_b32_e32 v213, 0xffff0000, v102
	v_lshlrev_b32_e32 v214, 16, v103
	v_and_b32_e32 v215, 0xffff0000, v103
	v_pk_mul_f32 v[222:223], v[110:111], v[190:191] op_sel_hi:[1,0]
	v_pk_mul_f32 v[224:225], v[118:119], v[190:191] op_sel_hi:[1,0]
	v_pk_fma_f32 v[212:213], v[222:223], v[252:253], v[212:213]
	v_pk_fma_f32 v[214:215], v[224:225], v[254:255], v[214:215]
	global_store_dwordx4 v234, v[212:215], s[38:39] offset:3072
	s_add_u32 s38, s38, 0x800000
	s_addc_u32 s39, s39, 0
	v_lshlrev_b32_e32 v208, 16, v120
	v_and_b32_e32 v209, 0xffff0000, v120
	v_lshlrev_b32_e32 v210, 16, v121
	v_and_b32_e32 v211, 0xffff0000, v121
	v_pk_mul_f32 v[222:223], v[128:129], v[186:187] op_sel_hi:[1,0]
	v_pk_mul_f32 v[224:225], v[136:137], v[186:187] op_sel_hi:[1,0]
	v_pk_fma_f32 v[208:209], v[222:223], v[240:241], v[208:209]
	v_pk_fma_f32 v[210:211], v[224:225], v[242:243], v[210:211]
	global_store_dwordx4 v234, v[208:211], s[38:39] offset:0
	v_lshlrev_b32_e32 v212, 16, v122
	v_and_b32_e32 v213, 0xffff0000, v122
	v_lshlrev_b32_e32 v214, 16, v123
	v_and_b32_e32 v215, 0xffff0000, v123
	v_pk_mul_f32 v[222:223], v[130:131], v[186:187] op_sel_hi:[1,0]
	v_pk_mul_f32 v[224:225], v[138:139], v[186:187] op_sel_hi:[1,0]
	v_pk_fma_f32 v[212:213], v[222:223], v[244:245], v[212:213]
	v_pk_fma_f32 v[214:215], v[224:225], v[246:247], v[214:215]
	global_store_dwordx4 v234, v[212:215], s[38:39] offset:1024
	v_lshlrev_b32_e32 v208, 16, v124
	v_and_b32_e32 v209, 0xffff0000, v124
	v_lshlrev_b32_e32 v210, 16, v125
	v_and_b32_e32 v211, 0xffff0000, v125
	v_pk_mul_f32 v[222:223], v[132:133], v[186:187] op_sel_hi:[1,0]
	v_pk_mul_f32 v[224:225], v[140:141], v[186:187] op_sel_hi:[1,0]
	v_pk_fma_f32 v[208:209], v[222:223], v[248:249], v[208:209]
	v_pk_fma_f32 v[210:211], v[224:225], v[250:251], v[210:211]
	global_store_dwordx4 v234, v[208:211], s[38:39] offset:2048
	v_lshlrev_b32_e32 v212, 16, v126
	v_and_b32_e32 v213, 0xffff0000, v126
	v_lshlrev_b32_e32 v214, 16, v127
	v_and_b32_e32 v215, 0xffff0000, v127
	v_pk_mul_f32 v[222:223], v[134:135], v[186:187] op_sel_hi:[1,0]
	v_pk_mul_f32 v[224:225], v[142:143], v[186:187] op_sel_hi:[1,0]
	v_pk_fma_f32 v[212:213], v[222:223], v[252:253], v[212:213]
	v_pk_fma_f32 v[214:215], v[224:225], v[254:255], v[214:215]
	global_store_dwordx4 v234, v[212:215], s[38:39] offset:3072
	s_add_u32 s38, s38, 0x800000
	s_addc_u32 s39, s39, 0
	s_waitcnt vmcnt(12)
	s_cmpk_lt_u32 s34, 0x200
	s_cbranch_scc0 .Lp10_nosamp_ld
; __device__ __forceinline__ float bf2f(unsigned b) { return __uint_as_float(b << 16); }
; __device__ __forceinline__ float sigmoidf_(float x) { return __builtin_amdgcn_rcpf(1.f + __expf(-x)); }
; __device__ __forceinline__ void row_final2(const FinPtrs (&r)[NR], const float* g, int lane) {
;     ...
;         for (int j = 0; j < 4; ++j) { { const u32x2 wv = ((const u32x2*)r[k].xin)[lane + 64 * j]; x[k][j] = (f32x4){bf2f(wv.x & 0xffffu), bf2f(wv.x >> 16), bf2f(wv.y & 0xffffu), bf2f(wv.y >> 16)}; }
;             ra[k][j] = ((const u32x2*)r[k].peb)[lane + 64 * j]; if (r[k].gls == nullptr) rb[k][j] = ((const u32x2*)r[k].glb)[lane + 64 * j]; }
; #pragma unroll
;     for (int k = 0; k < NR; ++k) { ss[k] = 0.f;
; #pragma unroll
;         for (int j = 0; j < 4; ++j) {
;             f32x4 pe, gl;
;             { const u32x2 a = ra[k][j]; pe = (f32x4){bf2f(a.x & 0xffffu), bf2f(a.x >> 16), bf2f(a.y & 0xffffu), bf2f(a.y >> 16)}; }
;             if (r[k].gls == nullptr) { const u32x2 b = rb[k][j]; gl = (f32x4){bf2f(b.x & 0xffffu), bf2f(b.x >> 16), bf2f(b.y & 0xffffu), bf2f(b.y >> 16)}; }
;             else { const float* gls = r[k].gls;
;                 gl = (((const f32x4*)gls)[lane + 64 * j] + ((const f32x4*)(gls + (size_t)TS * D))[lane + 64 * j]) + (((const f32x4*)(gls + (size_t)2 * TS * D))[lane + 64 * j] + ((const f32x4*)(gls + (size_t)3 * TS * D))[lane + 64 * j]); }
;             z[k][j] = (f32x4){pe.x * sigmoidf_(gl.x), pe.y * sigmoidf_(gl.y), pe.z * sigmoidf_(gl.z), pe.w * sigmoidf_(gl.w)};
;             ss[k] += (z[k][j].x * z[k][j].x + z[k][j].y * z[k][j].y) + (z[k][j].z * z[k][j].z + z[k][j].w * z[k][j].w);
	global_load_dwordx2 v[72:73], v232, s[36:37] offset:0
	global_load_dwordx2 v[74:75], v232, s[36:37] offset:512
	global_load_dwordx2 v[76:77], v232, s[36:37] offset:1024
	global_load_dwordx2 v[78:79], v232, s[36:37] offset:1536
	global_load_dwordx2 v[80:81], v233, s[36:37] offset:0
	global_load_dwordx2 v[82:83], v233, s[36:37] offset:512
	global_load_dwordx2 v[84:85], v233, s[36:37] offset:1024
	global_load_dwordx2 v[86:87], v233, s[36:37] offset:1536
	s_lshl_b32 s0, s34, 12
	s_add_u32 s44, s92, s0
	s_addc_u32 s45, s93, 0
	s_add_u32 s46, s44, 0x200000
	s_addc_u32 s47, s45, 0
	s_add_u32 s48, s44, 0x400000
	s_addc_u32 s49, s45, 0
	s_add_u32 s50, s44, 0x600000
	s_addc_u32 s51, s45, 0
	global_load_dwordx4 v[96:99], v234, s[44:45] offset:0
	global_load_dwordx4 v[100:103], v234, s[44:45] offset:1024
	global_load_dwordx4 v[104:107], v234, s[44:45] offset:2048
	global_load_dwordx4 v[108:111], v234, s[44:45] offset:3072
	global_load_dwordx4 v[112:115], v234, s[46:47] offset:0
	global_load_dwordx4 v[116:119], v234, s[46:47] offset:1024
	global_load_dwordx4 v[120:123], v234, s[46:47] offset:2048
	global_load_dwordx4 v[124:127], v234, s[46:47] offset:3072
	global_load_dwordx4 v[128:131], v234, s[48:49] offset:0
	global_load_dwordx4 v[132:135], v234, s[48:49] offset:1024
	global_load_dwordx4 v[136:139], v234, s[48:49] offset:2048
	global_load_dwordx4 v[140:143], v234, s[48:49] offset:3072
	global_load_dwordx4 v[144:147], v234, s[50:51] offset:0
	global_load_dwordx4 v[148:151], v234, s[50:51] offset:1024
	global_load_dwordx4 v[152:155], v234, s[50:51] offset:2048
	global_load_dwordx4 v[156:159], v234, s[50:51] offset:3072
.Lp10_nosamp_ld:
	v_mov_b32_e32 v192, 0
	v_mov_b32_e32 v193, 0
	v_mov_b32_e32 v194, 0
	v_mov_b32_e32 v195, 0
	v_lshlrev_b32_e32 v222, 16, v16
	v_and_b32_e32 v223, 0xffff0000, v16
	v_lshlrev_b32_e32 v224, 16, v17
	v_and_b32_e32 v225, 0xffff0000, v17
	v_pk_mul_f32 v[222:223], v[222:223], s[40:41]
	v_pk_mul_f32 v[224:225], v[224:225], s[40:41]
	v_exp_f32_e32 v222, v222
	v_exp_f32_e32 v223, v223
	v_exp_f32_e32 v224, v224
	v_exp_f32_e32 v225, v225
	v_pk_add_f32 v[222:223], v[222:223], s[42:43]
	v_pk_add_f32 v[224:225], v[224:225], s[42:43]
	v_rcp_f32_e32 v222, v222
	v_rcp_f32_e32 v223, v223
	v_rcp_f32_e32 v224, v224
	v_rcp_f32_e32 v225, v225
	v_lshlrev_b32_e32 v226, 16, v8
	v_and_b32_e32 v227, 0xffff0000, v8
	v_lshlrev_b32_e32 v228, 16, v9
	v_and_b32_e32 v229, 0xffff0000, v9
	v_pk_mul_f32 v[8:9], v[222:223], v[226:227]
	v_pk_mul_f32 v[16:17], v[224:225], v[228:229]
	v_pk_fma_f32 v[192:193], v[8:9], v[8:9], v[192:193]
	v_pk_fma_f32 v[194:195], v[16:17], v[16:17], v[194:195]
	v_lshlrev_b32_e32 v222, 16, v18
	v_and_b32_e32 v223, 0xffff0000, v18
	v_lshlrev_b32_e32 v224, 16, v19
	v_and_b32_e32 v225, 0xffff0000, v19
	v_pk_mul_f32 v[222:223], v[222:223], s[40:41]
	v_pk_mul_f32 v[224:225], v[224:225], s[40:41]
	v_exp_f32_e32 v222, v222
	v_exp_f32_e32 v223, v223
	v_exp_f32_e32 v224, v224
	v_exp_f32_e32 v225, v225
	v_pk_add_f32 v[222:223], v[222:223], s[42:43]
	v_pk_add_f32 v[224:225], v[224:225], s[42:43]
	v_rcp_f32_e32 v222, v222
	v_rcp_f32_e32 v223, v223
	v_rcp_f32_e32 v224, v224
	v_rcp_f32_e32 v225, v225
	v_lshlrev_b32_e32 v226, 16, v10
	v_and_b32_e32 v227, 0xffff0000, v10
	v_lshlrev_b32_e32 v228, 16, v11
	v_and_b32_e32 v229, 0xffff0000, v11
	v_pk_mul_f32 v[10:11], v[222:223], v[226:227]
	v_pk_mul_f32 v[18:19], v[224:225], v[228:229]
	v_pk_fma_f32 v[192:193], v[10:11], v[10:11], v[192:193]
	v_pk_fma_f32 v[194:195], v[18:19], v[18:19], v[194:195]
	v_lshlrev_b32_e32 v222, 16, v20
	v_and_b32_e32 v223, 0xffff0000, v20
	v_lshlrev_b32_e32 v224, 16, v21
	v_and_b32_e32 v225, 0xffff0000, v21
	v_pk_mul_f32 v[222:223], v[222:223], s[40:41]
	v_pk_mul_f32 v[224:225], v[224:225], s[40:41]
	v_exp_f32_e32 v222, v222
	v_exp_f32_e32 v223, v223
	v_exp_f32_e32 v224, v224
	v_exp_f32_e32 v225, v225
	v_pk_add_f32 v[222:223], v[222:223], s[42:43]
	v_pk_add_f32 v[224:225], v[224:225], s[42:43]
	v_rcp_f32_e32 v222, v222
	v_rcp_f32_e32 v223, v223
	v_rcp_f32_e32 v224, v224
	v_rcp_f32_e32 v225, v225
	v_lshlrev_b32_e32 v226, 16, v12
	v_and_b32_e32 v227, 0xffff0000, v12
	v_lshlrev_b32_e32 v228, 16, v13
	v_and_b32_e32 v229, 0xffff0000, v13
	v_pk_mul_f32 v[12:13], v[222:223], v[226:227]
	v_pk_mul_f32 v[20:21], v[224:225], v[228:229]
	v_pk_fma_f32 v[192:193], v[12:13], v[12:13], v[192:193]
	v_pk_fma_f32 v[194:195], v[20:21], v[20:21], v[194:195]
	v_lshlrev_b32_e32 v222, 16, v22
	v_and_b32_e32 v223, 0xffff0000, v22
	v_lshlrev_b32_e32 v224, 16, v23
	v_and_b32_e32 v225, 0xffff0000, v23
	v_pk_mul_f32 v[222:223], v[222:223], s[40:41]
	v_pk_mul_f32 v[224:225], v[224:225], s[40:41]
	v_exp_f32_e32 v222, v222
	v_exp_f32_e32 v223, v223
	v_exp_f32_e32 v224, v224
	v_exp_f32_e32 v225, v225
	v_pk_add_f32 v[222:223], v[222:223], s[42:43]
	v_pk_add_f32 v[224:225], v[224:225], s[42:43]
	v_rcp_f32_e32 v222, v222
	v_rcp_f32_e32 v223, v223
	v_rcp_f32_e32 v224, v224
	v_rcp_f32_e32 v225, v225
	v_lshlrev_b32_e32 v226, 16, v14
	v_and_b32_e32 v227, 0xffff0000, v14
	v_lshlrev_b32_e32 v228, 16, v15
	v_and_b32_e32 v229, 0xffff0000, v15
	v_pk_mul_f32 v[14:15], v[222:223], v[226:227]
	v_pk_mul_f32 v[22:23], v[224:225], v[228:229]
	v_pk_fma_f32 v[192:193], v[14:15], v[14:15], v[192:193]
	v_pk_fma_f32 v[194:195], v[22:23], v[22:23], v[194:195]
	v_mov_b32_e32 v196, 0
	v_mov_b32_e32 v197, 0
	v_mov_b32_e32 v198, 0
	v_mov_b32_e32 v199, 0
	v_lshlrev_b32_e32 v222, 16, v40
	v_and_b32_e32 v223, 0xffff0000, v40
	v_lshlrev_b32_e32 v224, 16, v41
	v_and_b32_e32 v225, 0xffff0000, v41
	v_pk_mul_f32 v[222:223], v[222:223], s[40:41]
	v_pk_mul_f32 v[224:225], v[224:225], s[40:41]
	v_exp_f32_e32 v222, v222
	v_exp_f32_e32 v223, v223
; __device__ __forceinline__ float bf2f(unsigned b) { return __uint_as_float(b << 16); }
; __device__ __forceinline__ float sigmoidf_(float x) { return __builtin_amdgcn_rcpf(1.f + __expf(-x)); }
; __device__ __forceinline__ void row_final2(const FinPtrs (&r)[NR], const float* g, int lane) {
;     ...
;     for (int k = 0; k < NR; ++k) { ss[k] = 0.f;
; #pragma unroll
;         for (int j = 0; j < 4; ++j) {
;             f32x4 pe, gl;
;             { const u32x2 a = ra[k][j]; pe = (f32x4){bf2f(a.x & 0xffffu), bf2f(a.x >> 16), bf2f(a.y & 0xffffu), bf2f(a.y >> 16)}; }
;             if (r[k].gls == nullptr) { const u32x2 b = rb[k][j]; gl = (f32x4){bf2f(b.x & 0xffffu), bf2f(b.x >> 16), bf2f(b.y & 0xffffu), bf2f(b.y >> 16)}; }
;             else { const float* gls = r[k].gls;
;                 gl = (((const f32x4*)gls)[lane + 64 * j] + ((const f32x4*)(gls + (size_t)TS * D))[lane + 64 * j]) + (((const f32x4*)(gls + (size_t)2 * TS * D))[lane + 64 * j] + ((const f32x4*)(gls + (size_t)3 * TS * D))[lane + 64 * j]); }
;             z[k][j] = (f32x4){pe.x * sigmoidf_(gl.x), pe.y * sigmoidf_(gl.y), pe.z * sigmoidf_(gl.z), pe.w * sigmoidf_(gl.w)};
;             ss[k] += (z[k][j].x * z[k][j].x + z[k][j].y * z[k][j].y) + (z[k][j].z * z[k][j].z + z[k][j].w * z[k][j].w);
;         } }
; #pragma unroll
;     for (int o = 1; o < 64; o <<= 1) {
; #pragma unroll
;             for (int k = 0; k < NR; ++k) ss[k] += __shfl_xor(ss[k], o); }
	v_exp_f32_e32 v224, v224
	v_exp_f32_e32 v225, v225
	v_pk_add_f32 v[222:223], v[222:223], s[42:43]
	v_pk_add_f32 v[224:225], v[224:225], s[42:43]
	v_rcp_f32_e32 v222, v222
	v_rcp_f32_e32 v223, v223
	v_rcp_f32_e32 v224, v224
	v_rcp_f32_e32 v225, v225
	v_lshlrev_b32_e32 v226, 16, v32
	v_and_b32_e32 v227, 0xffff0000, v32
	v_lshlrev_b32_e32 v228, 16, v33
	v_and_b32_e32 v229, 0xffff0000, v33
	v_pk_mul_f32 v[32:33], v[222:223], v[226:227]
	v_pk_mul_f32 v[40:41], v[224:225], v[228:229]
	v_pk_fma_f32 v[196:197], v[32:33], v[32:33], v[196:197]
	v_pk_fma_f32 v[198:199], v[40:41], v[40:41], v[198:199]
	v_lshlrev_b32_e32 v222, 16, v42
	v_and_b32_e32 v223, 0xffff0000, v42
	v_lshlrev_b32_e32 v224, 16, v43
	v_and_b32_e32 v225, 0xffff0000, v43
	v_pk_mul_f32 v[222:223], v[222:223], s[40:41]
	v_pk_mul_f32 v[224:225], v[224:225], s[40:41]
	v_exp_f32_e32 v222, v222
	v_exp_f32_e32 v223, v223
	v_exp_f32_e32 v224, v224
	v_exp_f32_e32 v225, v225
	v_pk_add_f32 v[222:223], v[222:223], s[42:43]
	v_pk_add_f32 v[224:225], v[224:225], s[42:43]
	v_rcp_f32_e32 v222, v222
	v_rcp_f32_e32 v223, v223
	v_rcp_f32_e32 v224, v224
	v_rcp_f32_e32 v225, v225
	v_lshlrev_b32_e32 v226, 16, v34
	v_and_b32_e32 v227, 0xffff0000, v34
	v_lshlrev_b32_e32 v228, 16, v35
	v_and_b32_e32 v229, 0xffff0000, v35
	v_pk_mul_f32 v[34:35], v[222:223], v[226:227]
	v_pk_mul_f32 v[42:43], v[224:225], v[228:229]
	v_pk_fma_f32 v[196:197], v[34:35], v[34:35], v[196:197]
	v_pk_fma_f32 v[198:199], v[42:43], v[42:43], v[198:199]
	v_lshlrev_b32_e32 v222, 16, v44
	v_and_b32_e32 v223, 0xffff0000, v44
	v_lshlrev_b32_e32 v224, 16, v45
	v_and_b32_e32 v225, 0xffff0000, v45
	v_pk_mul_f32 v[222:223], v[222:223], s[40:41]
	v_pk_mul_f32 v[224:225], v[224:225], s[40:41]
	v_exp_f32_e32 v222, v222
	v_exp_f32_e32 v223, v223
	v_exp_f32_e32 v224, v224
	v_exp_f32_e32 v225, v225
	v_pk_add_f32 v[222:223], v[222:223], s[42:43]
	v_pk_add_f32 v[224:225], v[224:225], s[42:43]
	v_rcp_f32_e32 v222, v222
	v_rcp_f32_e32 v223, v223
	v_rcp_f32_e32 v224, v224
	v_rcp_f32_e32 v225, v225
	v_lshlrev_b32_e32 v226, 16, v36
	v_and_b32_e32 v227, 0xffff0000, v36
	v_lshlrev_b32_e32 v228, 16, v37
	v_and_b32_e32 v229, 0xffff0000, v37
	v_pk_mul_f32 v[36:37], v[222:223], v[226:227]
	v_pk_mul_f32 v[44:45], v[224:225], v[228:229]
	v_pk_fma_f32 v[196:197], v[36:37], v[36:37], v[196:197]
	v_pk_fma_f32 v[198:199], v[44:45], v[44:45], v[198:199]
	v_lshlrev_b32_e32 v222, 16, v46
	v_and_b32_e32 v223, 0xffff0000, v46
	v_lshlrev_b32_e32 v224, 16, v47
	v_and_b32_e32 v225, 0xffff0000, v47
	v_pk_mul_f32 v[222:223], v[222:223], s[40:41]
	v_pk_mul_f32 v[224:225], v[224:225], s[40:41]
	v_exp_f32_e32 v222, v222
	v_exp_f32_e32 v223, v223
	v_exp_f32_e32 v224, v224
	v_exp_f32_e32 v225, v225
	v_pk_add_f32 v[222:223], v[222:223], s[42:43]
	v_pk_add_f32 v[224:225], v[224:225], s[42:43]
	v_rcp_f32_e32 v222, v222
	v_rcp_f32_e32 v223, v223
	v_rcp_f32_e32 v224, v224
	v_rcp_f32_e32 v225, v225
	v_lshlrev_b32_e32 v226, 16, v38
	v_and_b32_e32 v227, 0xffff0000, v38
	v_lshlrev_b32_e32 v228, 16, v39
	v_and_b32_e32 v229, 0xffff0000, v39
	v_pk_mul_f32 v[38:39], v[222:223], v[226:227]
	v_pk_mul_f32 v[46:47], v[224:225], v[228:229]
	v_pk_fma_f32 v[196:197], v[38:39], v[38:39], v[196:197]
	v_pk_fma_f32 v[198:199], v[46:47], v[46:47], v[198:199]
	v_pk_add_f32 v[192:193], v[192:193], v[194:195]
	v_pk_add_f32 v[196:197], v[196:197], v[198:199]
	v_add_f32_e32 v204, v192, v193
	v_add_f32_e32 v205, v196, v197
	ds_bpermute_b32 v192, v216, v204
	ds_bpermute_b32 v196, v216, v205
	s_waitcnt lgkmcnt(0)
	v_add_f32_e32 v204, v204, v192
	v_add_f32_e32 v205, v205, v196
	ds_bpermute_b32 v192, v217, v204
	ds_bpermute_b32 v196, v217, v205
	s_waitcnt lgkmcnt(0)
	v_add_f32_e32 v204, v204, v192
	v_add_f32_e32 v205, v205, v196
	ds_bpermute_b32 v192, v218, v204
	ds_bpermute_b32 v196, v218, v205
	s_waitcnt lgkmcnt(0)
	v_add_f32_e32 v204, v204, v192
	v_add_f32_e32 v205, v205, v196
	ds_bpermute_b32 v192, v219, v204
	ds_bpermute_b32 v196, v219, v205
	s_waitcnt lgkmcnt(0)
	v_add_f32_e32 v204, v204, v192
	v_add_f32_e32 v205, v205, v196
	ds_bpermute_b32 v192, v220, v204
	ds_bpermute_b32 v196, v220, v205
	s_waitcnt lgkmcnt(0)
	v_add_f32_e32 v204, v204, v192
	v_add_f32_e32 v205, v205, v196
	ds_bpermute_b32 v192, v221, v204
	ds_bpermute_b32 v196, v221, v205
	s_waitcnt lgkmcnt(0)
; __device__ __forceinline__ void row_final2(const FinPtrs (&r)[NR], const float* g, int lane) {
;     ...
;             for (int k = 0; k < NR; ++k) ss[k] += __shfl_xor(ss[k], o); }
; #pragma unroll
;     for (int k = 0; k < NR; ++k) { const float rs = rsqrtf(ss[k] * (1.f / D) + EPS);
; #pragma unroll
;         for (int j = 0; j < 4; ++j) { const f32x4 gv = ((const f32x4*)g)[lane + 64 * j]; ((f32x4*)r[k].yout)[lane + 64 * j] = x[k][j] + z[k][j] * rs * gv; } }
	v_add_f32_e32 v204, v204, v192
	v_add_f32_e32 v205, v205, v196
	v_fmamk_f32 v204, v204, 0x3a800000, v235
	v_fmamk_f32 v205, v205, 0x3a800000, v235
	v_rsq_f32_e32 v188, v204
	v_rsq_f32_e32 v190, v205
	s_nop 1
	v_lshlrev_b32_e32 v208, 16, v0
	v_and_b32_e32 v209, 0xffff0000, v0
	v_lshlrev_b32_e32 v210, 16, v1
	v_and_b32_e32 v211, 0xffff0000, v1
	v_pk_mul_f32 v[222:223], v[8:9], v[188:189] op_sel_hi:[1,0]
	v_pk_mul_f32 v[224:225], v[16:17], v[188:189] op_sel_hi:[1,0]
	v_pk_fma_f32 v[208:209], v[222:223], v[240:241], v[208:209]
	v_pk_fma_f32 v[210:211], v[224:225], v[242:243], v[210:211]
	global_store_dwordx4 v234, v[208:211], s[38:39] offset:0
	v_lshlrev_b32_e32 v212, 16, v2
	v_and_b32_e32 v213, 0xffff0000, v2
	v_lshlrev_b32_e32 v214, 16, v3
	v_and_b32_e32 v215, 0xffff0000, v3
	v_pk_mul_f32 v[222:223], v[10:11], v[188:189] op_sel_hi:[1,0]
	v_pk_mul_f32 v[224:225], v[18:19], v[188:189] op_sel_hi:[1,0]
	v_pk_fma_f32 v[212:213], v[222:223], v[244:245], v[212:213]
	v_pk_fma_f32 v[214:215], v[224:225], v[246:247], v[214:215]
	global_store_dwordx4 v234, v[212:215], s[38:39] offset:1024
	v_lshlrev_b32_e32 v208, 16, v4
	v_and_b32_e32 v209, 0xffff0000, v4
	v_lshlrev_b32_e32 v210, 16, v5
	v_and_b32_e32 v211, 0xffff0000, v5
	v_pk_mul_f32 v[222:223], v[12:13], v[188:189] op_sel_hi:[1,0]
	v_pk_mul_f32 v[224:225], v[20:21], v[188:189] op_sel_hi:[1,0]
	v_pk_fma_f32 v[208:209], v[222:223], v[248:249], v[208:209]
	v_pk_fma_f32 v[210:211], v[224:225], v[250:251], v[210:211]
	global_store_dwordx4 v234, v[208:211], s[38:39] offset:2048
	v_lshlrev_b32_e32 v212, 16, v6
	v_and_b32_e32 v213, 0xffff0000, v6
	v_lshlrev_b32_e32 v214, 16, v7
	v_and_b32_e32 v215, 0xffff0000, v7
	v_pk_mul_f32 v[222:223], v[14:15], v[188:189] op_sel_hi:[1,0]
	v_pk_mul_f32 v[224:225], v[22:23], v[188:189] op_sel_hi:[1,0]
	v_pk_fma_f32 v[212:213], v[222:223], v[252:253], v[212:213]
	v_pk_fma_f32 v[214:215], v[224:225], v[254:255], v[214:215]
	global_store_dwordx4 v234, v[212:215], s[38:39] offset:3072
	s_add_u32 s38, s38, 0x800000
	s_addc_u32 s39, s39, 0
	v_lshlrev_b32_e32 v208, 16, v24
	v_and_b32_e32 v209, 0xffff0000, v24
	v_lshlrev_b32_e32 v210, 16, v25
	v_and_b32_e32 v211, 0xffff0000, v25
	v_pk_mul_f32 v[222:223], v[32:33], v[190:191] op_sel_hi:[1,0]
	v_pk_mul_f32 v[224:225], v[40:41], v[190:191] op_sel_hi:[1,0]
	v_pk_fma_f32 v[208:209], v[222:223], v[240:241], v[208:209]
	v_pk_fma_f32 v[210:211], v[224:225], v[242:243], v[210:211]
	global_store_dwordx4 v234, v[208:211], s[38:39] offset:0
	v_lshlrev_b32_e32 v212, 16, v26
	v_and_b32_e32 v213, 0xffff0000, v26
	v_lshlrev_b32_e32 v214, 16, v27
	v_and_b32_e32 v215, 0xffff0000, v27
	v_pk_mul_f32 v[222:223], v[34:35], v[190:191] op_sel_hi:[1,0]
	v_pk_mul_f32 v[224:225], v[42:43], v[190:191] op_sel_hi:[1,0]
	v_pk_fma_f32 v[212:213], v[222:223], v[244:245], v[212:213]
	v_pk_fma_f32 v[214:215], v[224:225], v[246:247], v[214:215]
	global_store_dwordx4 v234, v[212:215], s[38:39] offset:1024
	v_lshlrev_b32_e32 v208, 16, v28
	v_and_b32_e32 v209, 0xffff0000, v28
	v_lshlrev_b32_e32 v210, 16, v29
	v_and_b32_e32 v211, 0xffff0000, v29
	v_pk_mul_f32 v[222:223], v[36:37], v[190:191] op_sel_hi:[1,0]
	v_pk_mul_f32 v[224:225], v[44:45], v[190:191] op_sel_hi:[1,0]
	v_pk_fma_f32 v[208:209], v[222:223], v[248:249], v[208:209]
	v_pk_fma_f32 v[210:211], v[224:225], v[250:251], v[210:211]
	global_store_dwordx4 v234, v[208:211], s[38:39] offset:2048
	v_lshlrev_b32_e32 v212, 16, v30
	v_and_b32_e32 v213, 0xffff0000, v30
	v_lshlrev_b32_e32 v214, 16, v31
	v_and_b32_e32 v215, 0xffff0000, v31
	v_pk_mul_f32 v[222:223], v[38:39], v[190:191] op_sel_hi:[1,0]
	v_pk_mul_f32 v[224:225], v[46:47], v[190:191] op_sel_hi:[1,0]
	v_pk_fma_f32 v[212:213], v[222:223], v[252:253], v[212:213]
	v_pk_fma_f32 v[214:215], v[224:225], v[254:255], v[214:215]
	global_store_dwordx4 v234, v[212:215], s[38:39] offset:3072
	s_add_u32 s38, s38, 0x800000
	s_addc_u32 s39, s39, 0
	s_cmpk_lt_u32 s34, 0x200
	s_cbranch_scc0 .LBB0_1282
; __device__ __forceinline__ float bf2f(unsigned b) { return __uint_as_float(b << 16); }
; __device__ __forceinline__ float sigmoidf_(float x) { return __builtin_amdgcn_rcpf(1.f + __expf(-x)); }
; __device__ __forceinline__ void row_final2(const FinPtrs (&r)[NR], const float* g, int lane) {
;     ...
;             f32x4 pe, gl;
;             { const u32x2 a = ra[k][j]; pe = (f32x4){bf2f(a.x & 0xffffu), bf2f(a.x >> 16), bf2f(a.y & 0xffffu), bf2f(a.y >> 16)}; }
;             if (r[k].gls == nullptr) { const u32x2 b = rb[k][j]; gl = (f32x4){bf2f(b.x & 0xffffu), bf2f(b.x >> 16), bf2f(b.y & 0xffffu), bf2f(b.y >> 16)}; }
;             else { const float* gls = r[k].gls;
;                 gl = (((const f32x4*)gls)[lane + 64 * j] + ((const f32x4*)(gls + (size_t)TS * D))[lane + 64 * j]) + (((const f32x4*)(gls + (size_t)2 * TS * D))[lane + 64 * j] + ((const f32x4*)(gls + (size_t)3 * TS * D))[lane + 64 * j]); }
;             z[k][j] = (f32x4){pe.x * sigmoidf_(gl.x), pe.y * sigmoidf_(gl.y), pe.z * sigmoidf_(gl.z), pe.w * sigmoidf_(gl.w)};
;             ss[k] += (z[k][j].x * z[k][j].x + z[k][j].y * z[k][j].y) + (z[k][j].z * z[k][j].z + z[k][j].w * z[k][j].w);
;         } }
; #pragma unroll
;     for (int o = 1; o < 64; o <<= 1) {
; #pragma unroll
;             for (int k = 0; k < NR; ++k) ss[k] += __shfl_xor(ss[k], o); }
; #pragma unroll
;     for (int k = 0; k < NR; ++k) { const float rs = rsqrtf(ss[k] * (1.f / D) + EPS);
; #pragma unroll
;         for (int j = 0; j < 4; ++j) { const f32x4 gv = ((const f32x4*)g)[lane + 64 * j]; ((f32x4*)r[k].yout)[lane + 64 * j] = x[k][j] + z[k][j] * rs * gv; } }
	s_waitcnt vmcnt(8)
	v_mov_b32_e32 v192, 0
	v_mov_b32_e32 v193, 0
	v_mov_b32_e32 v194, 0
	v_mov_b32_e32 v195, 0
	v_pk_add_f32 v[96:97], v[96:97], v[112:113]
	v_pk_add_f32 v[128:129], v[128:129], v[144:145]
	v_pk_add_f32 v[98:99], v[98:99], v[114:115]
	v_pk_add_f32 v[130:131], v[130:131], v[146:147]
	v_pk_add_f32 v[222:223], v[96:97], v[128:129]
	v_pk_add_f32 v[224:225], v[98:99], v[130:131]
	v_pk_mul_f32 v[222:223], v[222:223], s[40:41]
	v_pk_mul_f32 v[224:225], v[224:225], s[40:41]
	v_exp_f32_e32 v222, v222
	v_exp_f32_e32 v223, v223
	v_exp_f32_e32 v224, v224
	v_exp_f32_e32 v225, v225
	v_pk_add_f32 v[222:223], v[222:223], s[42:43]
	v_pk_add_f32 v[224:225], v[224:225], s[42:43]
	v_rcp_f32_e32 v222, v222
	v_rcp_f32_e32 v223, v223
	v_rcp_f32_e32 v224, v224
	v_rcp_f32_e32 v225, v225
	v_lshlrev_b32_e32 v226, 16, v80
	v_and_b32_e32 v227, 0xffff0000, v80
	v_lshlrev_b32_e32 v228, 16, v81
	v_and_b32_e32 v229, 0xffff0000, v81
	v_pk_mul_f32 v[96:97], v[222:223], v[226:227]
	v_pk_mul_f32 v[98:99], v[224:225], v[228:229]
	v_pk_fma_f32 v[192:193], v[96:97], v[96:97], v[192:193]
	v_pk_fma_f32 v[194:195], v[98:99], v[98:99], v[194:195]
	v_pk_add_f32 v[100:101], v[100:101], v[116:117]
	v_pk_add_f32 v[132:133], v[132:133], v[148:149]
	v_pk_add_f32 v[102:103], v[102:103], v[118:119]
	v_pk_add_f32 v[134:135], v[134:135], v[150:151]
	v_pk_add_f32 v[222:223], v[100:101], v[132:133]
	v_pk_add_f32 v[224:225], v[102:103], v[134:135]
	v_pk_mul_f32 v[222:223], v[222:223], s[40:41]
	v_pk_mul_f32 v[224:225], v[224:225], s[40:41]
	v_exp_f32_e32 v222, v222
	v_exp_f32_e32 v223, v223
	v_exp_f32_e32 v224, v224
	v_exp_f32_e32 v225, v225
	v_pk_add_f32 v[222:223], v[222:223], s[42:43]
	v_pk_add_f32 v[224:225], v[224:225], s[42:43]
	v_rcp_f32_e32 v222, v222
	v_rcp_f32_e32 v223, v223
	v_rcp_f32_e32 v224, v224
	v_rcp_f32_e32 v225, v225
	v_lshlrev_b32_e32 v226, 16, v82
	v_and_b32_e32 v227, 0xffff0000, v82
	v_lshlrev_b32_e32 v228, 16, v83
	v_and_b32_e32 v229, 0xffff0000, v83
	v_pk_mul_f32 v[100:101], v[222:223], v[226:227]
	v_pk_mul_f32 v[102:103], v[224:225], v[228:229]
	v_pk_fma_f32 v[192:193], v[100:101], v[100:101], v[192:193]
	v_pk_fma_f32 v[194:195], v[102:103], v[102:103], v[194:195]
	v_pk_add_f32 v[104:105], v[104:105], v[120:121]
	v_pk_add_f32 v[136:137], v[136:137], v[152:153]
	v_pk_add_f32 v[106:107], v[106:107], v[122:123]
	v_pk_add_f32 v[138:139], v[138:139], v[154:155]
	v_pk_add_f32 v[222:223], v[104:105], v[136:137]
	v_pk_add_f32 v[224:225], v[106:107], v[138:139]
	v_pk_mul_f32 v[222:223], v[222:223], s[40:41]
	v_pk_mul_f32 v[224:225], v[224:225], s[40:41]
	v_exp_f32_e32 v222, v222
	v_exp_f32_e32 v223, v223
	v_exp_f32_e32 v224, v224
	v_exp_f32_e32 v225, v225
	v_pk_add_f32 v[222:223], v[222:223], s[42:43]
	v_pk_add_f32 v[224:225], v[224:225], s[42:43]
	v_rcp_f32_e32 v222, v222
	v_rcp_f32_e32 v223, v223
	v_rcp_f32_e32 v224, v224
	v_rcp_f32_e32 v225, v225
	v_lshlrev_b32_e32 v226, 16, v84
	v_and_b32_e32 v227, 0xffff0000, v84
	v_lshlrev_b32_e32 v228, 16, v85
	v_and_b32_e32 v229, 0xffff0000, v85
	v_pk_mul_f32 v[104:105], v[222:223], v[226:227]
	v_pk_mul_f32 v[106:107], v[224:225], v[228:229]
	v_pk_fma_f32 v[192:193], v[104:105], v[104:105], v[192:193]
	v_pk_fma_f32 v[194:195], v[106:107], v[106:107], v[194:195]
	v_pk_add_f32 v[108:109], v[108:109], v[124:125]
	v_pk_add_f32 v[140:141], v[140:141], v[156:157]
	v_pk_add_f32 v[110:111], v[110:111], v[126:127]
	v_pk_add_f32 v[142:143], v[142:143], v[158:159]
	v_pk_add_f32 v[222:223], v[108:109], v[140:141]
	v_pk_add_f32 v[224:225], v[110:111], v[142:143]
	v_pk_mul_f32 v[222:223], v[222:223], s[40:41]
	v_pk_mul_f32 v[224:225], v[224:225], s[40:41]
	v_exp_f32_e32 v222, v222
	v_exp_f32_e32 v223, v223
	v_exp_f32_e32 v224, v224
	v_exp_f32_e32 v225, v225
	v_pk_add_f32 v[222:223], v[222:223], s[42:43]
	v_pk_add_f32 v[224:225], v[224:225], s[42:43]
	v_rcp_f32_e32 v222, v222
	v_rcp_f32_e32 v223, v223
	v_rcp_f32_e32 v224, v224
	v_rcp_f32_e32 v225, v225
	v_lshlrev_b32_e32 v226, 16, v86
	v_and_b32_e32 v227, 0xffff0000, v86
	v_lshlrev_b32_e32 v228, 16, v87
	v_and_b32_e32 v229, 0xffff0000, v87
	v_pk_mul_f32 v[108:109], v[222:223], v[226:227]
	v_pk_mul_f32 v[110:111], v[224:225], v[228:229]
	v_pk_fma_f32 v[192:193], v[108:109], v[108:109], v[192:193]
	v_pk_fma_f32 v[194:195], v[110:111], v[110:111], v[194:195]
	v_pk_add_f32 v[192:193], v[192:193], v[194:195]
	v_add_f32_e32 v204, v192, v193
	ds_bpermute_b32 v192, v216, v204
	s_waitcnt lgkmcnt(0)
	v_add_f32_e32 v204, v204, v192
	ds_bpermute_b32 v192, v217, v204
	s_waitcnt lgkmcnt(0)
	v_add_f32_e32 v204, v204, v192
	ds_bpermute_b32 v192, v218, v204
	s_waitcnt lgkmcnt(0)
	v_add_f32_e32 v204, v204, v192
	ds_bpermute_b32 v192, v219, v204
	s_waitcnt lgkmcnt(0)
	v_add_f32_e32 v204, v204, v192
	ds_bpermute_b32 v192, v220, v204
	s_waitcnt lgkmcnt(0)
	v_add_f32_e32 v204, v204, v192
	ds_bpermute_b32 v192, v221, v204
	s_waitcnt lgkmcnt(0)
	v_add_f32_e32 v204, v204, v192
	v_fmamk_f32 v204, v204, 0x3a800000, v235
	v_rsq_f32_e32 v188, v204
	s_nop 1
	v_lshlrev_b32_e32 v208, 16, v72
	v_and_b32_e32 v209, 0xffff0000, v72
	v_lshlrev_b32_e32 v210, 16, v73
	v_and_b32_e32 v211, 0xffff0000, v73
	v_pk_mul_f32 v[222:223], v[96:97], v[188:189] op_sel_hi:[1,0]
	v_pk_mul_f32 v[224:225], v[98:99], v[188:189] op_sel_hi:[1,0]
	v_pk_fma_f32 v[208:209], v[222:223], v[240:241], v[208:209]
	v_pk_fma_f32 v[210:211], v[224:225], v[242:243], v[210:211]
	global_store_dwordx4 v234, v[208:211], s[38:39] offset:0
	v_lshlrev_b32_e32 v212, 16, v74
	v_and_b32_e32 v213, 0xffff0000, v74
	v_lshlrev_b32_e32 v214, 16, v75
	v_and_b32_e32 v215, 0xffff0000, v75
	v_pk_mul_f32 v[222:223], v[100:101], v[188:189] op_sel_hi:[1,0]
	v_pk_mul_f32 v[224:225], v[102:103], v[188:189] op_sel_hi:[1,0]
	v_pk_fma_f32 v[212:213], v[222:223], v[244:245], v[212:213]
	v_pk_fma_f32 v[214:215], v[224:225], v[246:247], v[214:215]
	global_store_dwordx4 v234, v[212:215], s[38:39] offset:1024
	v_lshlrev_b32_e32 v208, 16, v76
	v_and_b32_e32 v209, 0xffff0000, v76
	v_lshlrev_b32_e32 v210, 16, v77
	v_and_b32_e32 v211, 0xffff0000, v77
	v_pk_mul_f32 v[222:223], v[104:105], v[188:189] op_sel_hi:[1,0]
	v_pk_mul_f32 v[224:225], v[106:107], v[188:189] op_sel_hi:[1,0]
	v_pk_fma_f32 v[208:209], v[222:223], v[248:249], v[208:209]
	v_pk_fma_f32 v[210:211], v[224:225], v[250:251], v[210:211]
	global_store_dwordx4 v234, v[208:211], s[38:39] offset:2048
	v_lshlrev_b32_e32 v212, 16, v78
	v_and_b32_e32 v213, 0xffff0000, v78
	v_lshlrev_b32_e32 v214, 16, v79
	v_and_b32_e32 v215, 0xffff0000, v79
	v_pk_mul_f32 v[222:223], v[108:109], v[188:189] op_sel_hi:[1,0]
	v_pk_mul_f32 v[224:225], v[110:111], v[188:189] op_sel_hi:[1,0]
	v_pk_fma_f32 v[212:213], v[222:223], v[252:253], v[212:213]
	v_pk_fma_f32 v[214:215], v[224:225], v[254:255], v[214:215]
	global_store_dwordx4 v234, v[212:215], s[38:39] offset:3072
	s_add_u32 s38, s38, 0x800000
	s_addc_u32 s39, s39, 0
